# v30 + hfin (HGRN output norm+gate) as 256 work-queue units at the end of the mixer phase (waits on a device counter of finished HGRN units); hfin phase has no work left
# speedup vs baseline: 1.0004x; 1.0003x over previous
; #define LAS __attribute__((address_space(3)))
; __device__ __forceinline__ int opaque_tid() { int t = threadIdx.x; asm volatile("" : "+v"(t)); return t; }
;     LAS unsigned char* lds = (LAS unsigned char*)lds_g;
;     unsigned* ctr = (unsigned*)(P.ws + WS_CTL) + CW_QUEUE + 64 * (l + DEPTH * rep);
;     volatile LAS int* slot = (volatile LAS int*)(lds + LDS_MISC);
;     const bool need_ctx = l < DEPTH - 1;
;     constexpr int N_H = 32, N_F = 128, N_A = 512, N_C = 256, N_FC = 16, N_AC = 64, N_CC = 32;
;     const int total = N_H + N_F + N_A + N_C + (need_ctx ? N_FC + N_AC + N_CC : 0);
;     for (;;) {
;         if (opaque_tid() == 0) *slot = (int)atomicAdd(ctr, 1u);
;         __syncthreads();
;         int it = *slot;
;         __syncthreads();
;         if (it >= total) break;
; __device__ __forceinline__ void phase_hfin(const Params& P, int l) {
;     const float* od0 = (const float*)(P.ws + WS_ODIR); const float* od1 = od0 + (size_t)ROWS * 256;
;     const bf16_t* proj = (const bf16_t*)(P.ws + WS_PROJ); bf16_t* mix = (bf16_t*)(P.ws + WS_H);
;     const float* gn = P.hgrn_norm + (size_t)l * 64;
;     const long total = (long)ROWS * 4 * 16;
;     const int tid = opaque_tid(), lane = tid & 63;
;     const long S = (long)gridDim.x * 512;
;     const int sub = tid & 15; const f32x4 gg = *(const f32x4*)(gn + sub * 4);
;     for (long i0 = (long)blockIdx.x * 512 + tid; i0 < total; i0 += 3 * S) {
;         f32x4 a[3], b2[3]; u32x2 gw[3];
; #pragma unroll
;         for (int u = 0; u < 3; ++u) {
;             const long i = i0 + u * S; const bool ok = i < total; const long rh = (ok ? i : i0) >> 4; const int h = (int)(rh & 3); const long r = rh >> 2;
;             const size_t off = (size_t)r * 256 + h * 64 + sub * 4;
;             a[u] = *(const f32x4*)(od0 + off); b2[u] = *(const f32x4*)(od1 + off);
;             gw[u] = *(const u32x2*)(proj + (size_t)r * INW + PB_G + h * 64 + sub * 4);
;         }
.LBB0_347:
	s_or_b64 exec, exec, s[0:1]
	v_readlane_b32 s12, v255, 0
	s_waitcnt lgkmcnt(0)
	s_barrier
	s_cmp_lg_u32 s12, 3
	s_load_dwordx2 s[8:9], s[28:29], 0x48
	s_load_dwordx2 s[54:55], s[28:29], 0xa0
	s_cselect_b64 s[0:1], -1, 0
	v_readlane_b32 s13, v255, 1
	v_writelane_b32 v255, s0, 3
	s_lshl_b32 s64, s12, 6
	s_cmp_eq_u32 s12, 3
	v_writelane_b32 v255, s1, 4
	s_movk_i32 s0, 0x3a0
	s_cselect_b32 s29, s0, 0x410
	s_cmp_eq_u32 s60, 0x100
	s_cselect_b32 s0, 0x100, 0
	s_add_u32 s29, s29, s0
	s_lshl_b64 s[18:19], s[12:13], 8
	s_lshl_b64 s[0:1], s[64:65], 2
	s_waitcnt lgkmcnt(0)
	s_add_u32 s58, s54, s0
	s_addc_u32 s59, s55, s1
	s_add_u32 s56, s54, 0x9d00000
	s_addc_u32 s57, s55, 0
	s_add_u32 s20, s54, 0x17500000
	s_addc_u32 s0, s55, 0
	v_writelane_b32 v255, s0, 5
	s_add_u32 s0, s54, 0x5500000
	s_addc_u32 s1, s55, 0
	v_writelane_b32 v255, s0, 6
	s_nop 1
	v_writelane_b32 v255, s1, 7
	s_add_u32 s0, s54, 0x16300000
	v_writelane_b32 v255, s0, 8
	s_addc_u32 s0, s55, 0
	v_writelane_b32 v255, s0, 9
	s_lshl_b64 s[0:1], s[12:13], 2
	s_add_u32 s10, s54, s0
	s_addc_u32 s11, s55, s1
	s_add_u32 s0, s10, 0x1000
	s_addc_u32 s1, s11, 0
	v_writelane_b32 v255, s0, 10
	s_nop 1
	v_writelane_b32 v255, s1, 11
	s_add_u32 s0, s10, 0x1020
	s_addc_u32 s1, s11, 0
	v_writelane_b32 v255, s0, 12
	s_add_u32 s24, s8, s18
	s_nop 0
	v_writelane_b32 v255, s1, 13
	v_writelane_b32 v255, s18, 14
	s_addc_u32 s25, s9, s19
	s_add_u32 s0, s54, 0x4400000
	s_addc_u32 s1, s55, 0
	v_writelane_b32 v255, s19, 15
	s_add_u32 s7, s54, 0x19e00000
	v_writelane_b32 v255, s7, 16
	s_addc_u32 s7, s55, 0
	v_writelane_b32 v255, s7, 17
	s_add_u32 s7, s54, 0x5500600
	v_writelane_b32 v255, s7, 18
	s_addc_u32 s7, s55, 0
	s_add_u32 s8, s54, 0x4420000
	v_writelane_b32 v255, s7, 19
	s_addc_u32 s9, s55, 0
	v_writelane_b32 v255, s8, 20
	s_nop 1
	v_writelane_b32 v255, s9, 21
	s_add_u32 s8, s54, 0x4400080
	s_addc_u32 s9, s55, 0
	v_writelane_b32 v255, s8, 22
	s_nop 1
	v_writelane_b32 v255, s9, 23
	s_mul_i32 s9, s12, 0x3fc
	s_mul_hi_u32 s8, s12, 0x3fc
	s_add_u32 s10, s10, s9
	s_addc_u32 s11, s11, s8
	v_writelane_b32 v255, s10, 24
	s_add_u32 s8, s54, 0x1a200000
	s_addc_u32 s9, s55, 0
	v_writelane_b32 v255, s11, 25
	v_writelane_b32 v255, s8, 26
	s_add_u32 s7, s54, 0x3400000
	s_nop 0
	v_writelane_b32 v255, s9, 27
	v_writelane_b32 v255, s7, 28
	s_addc_u32 s7, s55, 0
	v_writelane_b32 v255, s7, 30
	s_add_u32 s7, s54, 0x17e00000
	v_writelane_b32 v255, s7, 32
	s_addc_u32 s7, s55, 0
	v_writelane_b32 v255, s7, 34
	s_add_u32 s7, s54, 0x5580600
	v_writelane_b32 v255, s7, 38
	s_addc_u32 s36, s55, 0
	s_branch .LBB0_351
.Lhfu_unit:
	v_readlane_b32 s18, v254, 55
	v_readlane_b32 s19, v254, 56
	v_readlane_b32 s7, v255, 0
	v_readfirstlane_b32 s100, v200
	s_nop 3
	s_load_dwordx2 s[10:11], s[18:19], 0xa0
	s_load_dwordx2 s[8:9], s[18:19], 0x58
	s_sub_u32 s12, s29, 0x100
	s_sub_u32 s12, s37, s12
	s_mul_i32 s12, s12, 0x90
	s_lshr_b32 s100, s100, 6
	s_add_u32 s101, s12, s100
	s_add_u32 s15, s12, 0x8f
	s_add_u32 s7, s7, 1
	s_lshl_b32 s7, s7, 5
	s_mov_b32 s13, 0
	s_waitcnt lgkmcnt(0)
.Lhfu_spin:
	global_load_dword v0, v129, s[10:11] offset:576 sc1
	s_waitcnt vmcnt(0)
	v_readfirstlane_b32 s12, v0
	s_nop 3
	s_cmp_ge_u32 s12, s7
	s_cbranch_scc1 .Lhfu_go
	s_sleep 4
	s_add_u32 s13, s13, 1
	s_cmp_lt_u32 s13, 0x8000
	s_cbranch_scc1 .Lhfu_spin
.Lhfu_go:
	buffer_inv sc1
	s_waitcnt vmcnt(0)
	v_readlane_b32 s12, v255, 14
	v_readlane_b32 s13, v255, 15
	v_and_b32_e32 v64, 63, v200
	v_and_b32_e32 v66, 15, v200
	v_lshlrev_b32_e32 v66, 4, v66
	v_lshlrev_b32_e32 v65, 3, v64
	v_lshlrev_b32_e32 v76, 2, v64
	v_xor_b32_e32 v67, 4, v76
	v_xor_b32_e32 v68, 8, v76
	v_xor_b32_e32 v69, 16, v76
	v_xor_b32_e32 v70, 32, v76
	v_lshlrev_b32_e32 v64, 4, v64
	s_add_u32 s8, s8, s12
	s_addc_u32 s9, s9, s13
	global_load_dwordx4 v[60:63], v66, s[8:9]
	s_add_u32 s46, s10, 0x1a200000
	s_addc_u32 s47, s11, 0
	s_add_u32 s48, s10, 0x1c600000
	s_addc_u32 s49, s11, 0
	s_add_u32 s38, s10, 0x9d00e00
	s_addc_u32 s39, s11, 0
	s_add_u32 s40, s10, 0x5500200
	s_addc_u32 s41, s11, 0
	s_lshl_b32 s12, s101, 10
	s_add_u32 s8, s46, s12
	s_addc_u32 s9, s47, 0
	global_load_dwordx4 v[0:3], v64, s[8:9]
	s_add_u32 s8, s48, s12
	s_addc_u32 s9, s49, 0
	global_load_dwordx4 v[4:7], v64, s[8:9]
	s_mul_i32 s12, s101, 0x1600
	s_add_u32 s8, s38, s12
	s_addc_u32 s9, s39, 0
	global_load_dwordx2 v[8:9], v65, s[8:9]
	s_add_u32 s100, s101, 8
	s_cmp_le_u32 s100, s15
	s_cselect_b32 s100, s100, s101
	s_lshl_b32 s12, s100, 10
	s_add_u32 s8, s46, s12
	s_addc_u32 s9, s47, 0
	global_load_dwordx4 v[10:13], v64, s[8:9]
	s_add_u32 s8, s48, s12
	s_addc_u32 s9, s49, 0
	global_load_dwordx4 v[14:17], v64, s[8:9]
	s_mul_i32 s12, s100, 0x1600
	s_add_u32 s8, s38, s12
	s_addc_u32 s9, s39, 0
	global_load_dwordx2 v[18:19], v65, s[8:9]
	s_mul_i32 s100, 8, 2
	s_add_u32 s100, s100, s101
	s_cmp_le_u32 s100, s15
	s_cselect_b32 s100, s100, s101
	s_lshl_b32 s12, s100, 10
	s_add_u32 s8, s46, s12
	s_addc_u32 s9, s47, 0
	global_load_dwordx4 v[20:23], v64, s[8:9]
	s_add_u32 s8, s48, s12
	s_addc_u32 s9, s49, 0
	global_load_dwordx4 v[24:27], v64, s[8:9]
	s_mul_i32 s12, s100, 0x1600
	s_add_u32 s8, s38, s12
	s_addc_u32 s9, s39, 0
	global_load_dwordx2 v[28:29], v65, s[8:9]
	s_mul_i32 s100, 8, 3
	s_add_u32 s100, s100, s101
	s_cmp_le_u32 s100, s15
	s_cselect_b32 s100, s100, s101
	s_lshl_b32 s12, s100, 10
	s_add_u32 s8, s46, s12
	s_addc_u32 s9, s47, 0
	global_load_dwordx4 v[30:33], v64, s[8:9]
	s_add_u32 s8, s48, s12
	s_addc_u32 s9, s49, 0
	global_load_dwordx4 v[34:37], v64, s[8:9]
	s_mul_i32 s12, s100, 0x1600
	s_add_u32 s8, s38, s12
	s_addc_u32 s9, s39, 0
	global_load_dwordx2 v[38:39], v65, s[8:9]
	s_mul_i32 s100, 8, 4
	s_add_u32 s100, s100, s101
	s_cmp_le_u32 s100, s15
	s_cselect_b32 s100, s100, s101
	s_lshl_b32 s12, s100, 10
	s_add_u32 s8, s46, s12
	s_addc_u32 s9, s47, 0
	global_load_dwordx4 v[40:43], v64, s[8:9]
	s_add_u32 s8, s48, s12
	s_addc_u32 s9, s49, 0
	global_load_dwordx4 v[44:47], v64, s[8:9]
	s_mul_i32 s12, s100, 0x1600
	s_add_u32 s8, s38, s12
	s_addc_u32 s9, s39, 0
	global_load_dwordx2 v[48:49], v65, s[8:9]
	s_mul_i32 s100, 8, 5
	s_add_u32 s100, s100, s101
	s_cmp_le_u32 s100, s15
	s_cselect_b32 s100, s100, s101
	s_lshl_b32 s12, s100, 10
	s_add_u32 s8, s46, s12
	s_addc_u32 s9, s47, 0
	global_load_dwordx4 v[50:53], v64, s[8:9]
	s_add_u32 s8, s48, s12
	s_addc_u32 s9, s49, 0
	global_load_dwordx4 v[54:57], v64, s[8:9]
	s_mul_i32 s12, s100, 0x1600
	s_add_u32 s8, s38, s12
	s_addc_u32 s9, s39, 0
	global_load_dwordx2 v[58:59], v65, s[8:9]
	s_waitcnt vmcnt(15)
; __device__ __forceinline__ unsigned pk2(float lo, float hi) { f32x2_t v = {lo, hi}; bf16x2_t b = __builtin_convertvector(v, bf16x2_t); return __builtin_bit_cast(unsigned, b); }
; __device__ __forceinline__ float shx(float v, int o, int lane) { return __builtin_bit_cast(float, __builtin_amdgcn_ds_bpermute((lane ^ o) << 2, __builtin_bit_cast(int, v))); }
; __device__ __forceinline__ float sigmoidf_(float z) { return __builtin_amdgcn_rcpf(1.0f + fast_exp2(-z * LOG2E)); }
; __device__ __forceinline__ void phase_hfin(const Params& P, int l) {
;     ...
;         for (int u = 0; u < 3; ++u) {
;             const long i = i0 + u * S; const bool ok = i < total; const long rh = (ok ? i : i0) >> 4; const int h = (int)(rh & 3); const long r = rh >> 2;
;             const size_t off = (size_t)r * 256 + h * 64 + sub * 4;
;             a[u] = *(const f32x4*)(od0 + off); b2[u] = *(const f32x4*)(od1 + off);
;             gw[u] = *(const u32x2*)(proj + (size_t)r * INW + PB_G + h * 64 + sub * 4);
;         }
; #pragma unroll
;         for (int u = 0; u < 3; ++u) {
;             const long i = i0 + u * S; if (i >= total) break;
;             const long rh = i >> 4; const int h = (int)(rh & 3); const long r = rh >> 2;
;             const f32x4 o = a[u] + b2[u];
;             float ss = (o.x * o.x + o.y * o.y) + (o.z * o.z + o.w * o.w);
;             ss += shx(ss, 1, lane); ss += shx(ss, 2, lane); ss += shx(ss, 4, lane); ss += shx(ss, 8, lane);
;             const float rs = 1.0f / sqrtf(ss * (1.0f / 64.0f) + RMS_EPS);
;             const float g0 = bflo(gw[u].x), g1 = bfhi(gw[u].x), g2 = bflo(gw[u].y), g3 = bfhi(gw[u].y);
;             u32x2 w; w.x = pk2(o.x * rs * gg.x * (g0 * sigmoidf_(g0)), o.y * rs * gg.y * (g1 * sigmoidf_(g1))); w.y = pk2(o.z * rs * gg.z * (g2 * sigmoidf_(g2)), o.w * rs * gg.w * (g3 * sigmoidf_(g3)));
;             *(u32x2*)(mix + (size_t)r * DM + 256 + h * 64 + sub * 4) = w;
	v_add_f32_e32 v72, v0, v4
	v_add_f32_e32 v73, v1, v5
	v_add_f32_e32 v74, v2, v6
	v_add_f32_e32 v75, v3, v7
	v_lshlrev_b32_e32 v84, 16, v8
	v_and_b32_e32 v85, 0xffff0000, v8
	v_lshlrev_b32_e32 v86, 16, v9
	v_and_b32_e32 v87, 0xffff0000, v9
	v_mul_f32_e32 v76, v73, v73
	v_mul_f32_e32 v77, v75, v75
	v_fmac_f32_e32 v76, v72, v72
	v_fmac_f32_e32 v77, v74, v74
	v_add_f32_e32 v78, v76, v77
	ds_bpermute_b32 v76, v67, v78
	v_mul_f32_e32 v88, 0xbfb8aa3b, v84
	v_mul_f32_e32 v89, 0xbfb8aa3b, v85
	v_mul_f32_e32 v90, 0xbfb8aa3b, v86
	v_mul_f32_e32 v91, 0xbfb8aa3b, v87
	s_waitcnt lgkmcnt(0)
	v_add_f32_e32 v78, v78, v76
	ds_bpermute_b32 v76, v68, v78
	v_exp_f32_e32 v88, v88
	v_exp_f32_e32 v89, v89
	v_exp_f32_e32 v90, v90
	v_exp_f32_e32 v91, v91
	s_waitcnt lgkmcnt(0)
	v_add_f32_e32 v78, v78, v76
	ds_bpermute_b32 v76, v69, v78
	v_add_f32_e32 v88, 1.0, v88
	v_add_f32_e32 v89, 1.0, v89
	v_add_f32_e32 v90, 1.0, v90
	v_add_f32_e32 v91, 1.0, v91
	s_waitcnt lgkmcnt(0)
	v_add_f32_e32 v78, v78, v76
	ds_bpermute_b32 v76, v70, v78
	v_rcp_f32_e32 v88, v88
	v_rcp_f32_e32 v89, v89
	v_rcp_f32_e32 v90, v90
	v_rcp_f32_e32 v91, v91
	s_waitcnt lgkmcnt(0)
	v_add_f32_e32 v78, v78, v76
	v_mul_f32_e32 v88, v88, v84
	v_mul_f32_e32 v89, v89, v85
	v_mul_f32_e32 v90, v90, v86
	v_mul_f32_e32 v91, v91, v87
	v_fmamk_f32 v78, v78, 0x3c800000, v201
	v_mul_f32_e32 v76, 0x4f800000, v78
	v_cmp_gt_f32_e32 vcc, 0xf800000, v78
	s_nop 1
	v_cndmask_b32_e32 v78, v78, v76, vcc
	v_sqrt_f32_e32 v76, v78
	s_nop 0
	v_add_u32_e32 v79, -1, v76
	v_add_u32_e32 v80, 1, v76
	v_fma_f32 v81, -v79, v76, v78
	v_fma_f32 v82, -v80, v76, v78
	v_cmp_ge_f32_e64 s[42:43], 0, v81
	s_nop 1
	v_cndmask_b32_e64 v76, v76, v79, s[42:43]
	v_cmp_lt_f32_e64 s[42:43], 0, v82
	s_nop 1
	v_cndmask_b32_e64 v76, v76, v80, s[42:43]
	v_mul_f32_e32 v79, 0x37800000, v76
	v_cndmask_b32_e32 v76, v76, v79, vcc
	v_cmp_class_f32_e32 vcc, v78, v202
	s_nop 1
	v_cndmask_b32_e32 v78, v76, v78, vcc
	v_div_scale_f32 v76, s[42:43], v78, v78, 1.0
	v_rcp_f32_e32 v79, v76
	v_div_scale_f32 v80, vcc, 1.0, v78, 1.0
	v_fma_f32 v81, -v76, v79, 1.0
	v_fmac_f32_e32 v79, v81, v79
	v_mul_f32_e32 v81, v80, v79
	v_fma_f32 v82, -v76, v81, v80
	v_fmac_f32_e32 v81, v82, v79
	v_fma_f32 v76, -v76, v81, v80
	v_div_fmas_f32 v76, v76, v79, v81
	v_div_fixup_f32 v83, v76, v78, 1.0
	v_mul_f32_e32 v92, v72, v83
	v_mul_f32_e32 v92, v60, v92
	v_mul_f32_e32 v92, v88, v92
	v_mul_f32_e32 v93, v73, v83
	v_mul_f32_e32 v93, v61, v93
	v_mul_f32_e32 v93, v89, v93
	v_mul_f32_e32 v94, v74, v83
	v_mul_f32_e32 v94, v62, v94
	v_mul_f32_e32 v94, v90, v94
	v_mul_f32_e32 v95, v75, v83
	v_mul_f32_e32 v95, v63, v95
	v_mul_f32_e32 v95, v91, v95
	v_cvt_pk_bf16_f32 v96, v92, v93
	v_cvt_pk_bf16_f32 v97, v94, v95
	s_lshl_b32 s12, s101, 11
	s_add_u32 s8, s40, s12
	s_addc_u32 s9, s41, 0
	global_store_dwordx2 v65, v[96:97], s[8:9]
	s_mul_i32 s100, 8, 6
	s_add_u32 s100, s100, s101
	s_cmp_le_u32 s100, s15
	s_cselect_b32 s100, s100, s101
	s_lshl_b32 s12, s100, 10
	s_add_u32 s8, s46, s12
	s_addc_u32 s9, s47, 0
	global_load_dwordx4 v[0:3], v64, s[8:9]
	s_add_u32 s8, s48, s12
	s_addc_u32 s9, s49, 0
	global_load_dwordx4 v[4:7], v64, s[8:9]
	s_mul_i32 s12, s100, 0x1600
	s_add_u32 s8, s38, s12
	s_addc_u32 s9, s39, 0
	global_load_dwordx2 v[8:9], v65, s[8:9]
	s_add_u32 s101, s101, 8
	s_cmp_gt_u32 s101, s15
	s_cbranch_scc1 .Lhfu_exit
	s_waitcnt vmcnt(16)
	v_add_f32_e32 v72, v10, v14
	v_add_f32_e32 v73, v11, v15
	v_add_f32_e32 v74, v12, v16
	v_add_f32_e32 v75, v13, v17
	v_lshlrev_b32_e32 v84, 16, v18
	v_and_b32_e32 v85, 0xffff0000, v18
	v_lshlrev_b32_e32 v86, 16, v19
	v_and_b32_e32 v87, 0xffff0000, v19
	v_mul_f32_e32 v76, v73, v73
	v_mul_f32_e32 v77, v75, v75
	v_fmac_f32_e32 v76, v72, v72
	v_fmac_f32_e32 v77, v74, v74
	v_add_f32_e32 v78, v76, v77
	ds_bpermute_b32 v76, v67, v78
	v_mul_f32_e32 v88, 0xbfb8aa3b, v84
	v_mul_f32_e32 v89, 0xbfb8aa3b, v85
	v_mul_f32_e32 v90, 0xbfb8aa3b, v86
	v_mul_f32_e32 v91, 0xbfb8aa3b, v87
	s_waitcnt lgkmcnt(0)
	v_add_f32_e32 v78, v78, v76
	ds_bpermute_b32 v76, v68, v78
	v_exp_f32_e32 v88, v88
	v_exp_f32_e32 v89, v89
	v_exp_f32_e32 v90, v90
	v_exp_f32_e32 v91, v91
	s_waitcnt lgkmcnt(0)
	v_add_f32_e32 v78, v78, v76
	ds_bpermute_b32 v76, v69, v78
	v_add_f32_e32 v88, 1.0, v88
	v_add_f32_e32 v89, 1.0, v89
	v_add_f32_e32 v90, 1.0, v90
	v_add_f32_e32 v91, 1.0, v91
	s_waitcnt lgkmcnt(0)
	v_add_f32_e32 v78, v78, v76
	ds_bpermute_b32 v76, v70, v78
	v_rcp_f32_e32 v88, v88
	v_rcp_f32_e32 v89, v89
	v_rcp_f32_e32 v90, v90
	v_rcp_f32_e32 v91, v91
	s_waitcnt lgkmcnt(0)
	v_add_f32_e32 v78, v78, v76
	v_mul_f32_e32 v88, v88, v84
	v_mul_f32_e32 v89, v89, v85
	v_mul_f32_e32 v90, v90, v86
	v_mul_f32_e32 v91, v91, v87
	v_fmamk_f32 v78, v78, 0x3c800000, v201
	v_mul_f32_e32 v76, 0x4f800000, v78
	v_cmp_gt_f32_e32 vcc, 0xf800000, v78
	s_nop 1
	v_cndmask_b32_e32 v78, v78, v76, vcc
	v_sqrt_f32_e32 v76, v78
	s_nop 0
	v_add_u32_e32 v79, -1, v76
	v_add_u32_e32 v80, 1, v76
	v_fma_f32 v81, -v79, v76, v78
	v_fma_f32 v82, -v80, v76, v78
	v_cmp_ge_f32_e64 s[42:43], 0, v81
	s_nop 1
	v_cndmask_b32_e64 v76, v76, v79, s[42:43]
	v_cmp_lt_f32_e64 s[42:43], 0, v82
	s_nop 1
	v_cndmask_b32_e64 v76, v76, v80, s[42:43]
	v_mul_f32_e32 v79, 0x37800000, v76
	v_cndmask_b32_e32 v76, v76, v79, vcc
	v_cmp_class_f32_e32 vcc, v78, v202
	s_nop 1
	v_cndmask_b32_e32 v78, v76, v78, vcc
	v_div_scale_f32 v76, s[42:43], v78, v78, 1.0
	v_rcp_f32_e32 v79, v76
	v_div_scale_f32 v80, vcc, 1.0, v78, 1.0
	v_fma_f32 v81, -v76, v79, 1.0
	v_fmac_f32_e32 v79, v81, v79
	v_mul_f32_e32 v81, v80, v79
	v_fma_f32 v82, -v76, v81, v80
	v_fmac_f32_e32 v81, v82, v79
	v_fma_f32 v76, -v76, v81, v80
	v_div_fmas_f32 v76, v76, v79, v81
	v_div_fixup_f32 v83, v76, v78, 1.0
	v_mul_f32_e32 v92, v72, v83
	v_mul_f32_e32 v92, v60, v92
	v_mul_f32_e32 v92, v88, v92
	v_mul_f32_e32 v93, v73, v83
	v_mul_f32_e32 v93, v61, v93
	v_mul_f32_e32 v93, v89, v93
	v_mul_f32_e32 v94, v74, v83
	v_mul_f32_e32 v94, v62, v94
	v_mul_f32_e32 v94, v90, v94
	v_mul_f32_e32 v95, v75, v83
	v_mul_f32_e32 v95, v63, v95
	v_mul_f32_e32 v95, v91, v95
	v_cvt_pk_bf16_f32 v96, v92, v93
	v_cvt_pk_bf16_f32 v97, v94, v95
	s_lshl_b32 s12, s101, 11
	s_add_u32 s8, s40, s12
	s_addc_u32 s9, s41, 0
	global_store_dwordx2 v65, v[96:97], s[8:9]
	s_mul_i32 s100, 8, 6
	s_add_u32 s100, s100, s101
	s_cmp_le_u32 s100, s15
	s_cselect_b32 s100, s100, s101
	s_lshl_b32 s12, s100, 10
	s_add_u32 s8, s46, s12
	s_addc_u32 s9, s47, 0
	global_load_dwordx4 v[10:13], v64, s[8:9]
	s_add_u32 s8, s48, s12
	s_addc_u32 s9, s49, 0
	global_load_dwordx4 v[14:17], v64, s[8:9]
	s_mul_i32 s12, s100, 0x1600
	s_add_u32 s8, s38, s12
	s_addc_u32 s9, s39, 0
	global_load_dwordx2 v[18:19], v65, s[8:9]
	s_add_u32 s101, s101, 8
	s_cmp_gt_u32 s101, s15
	s_cbranch_scc1 .Lhfu_exit
; __device__ __forceinline__ unsigned pk2(float lo, float hi) { f32x2_t v = {lo, hi}; bf16x2_t b = __builtin_convertvector(v, bf16x2_t); return __builtin_bit_cast(unsigned, b); }
; __device__ __forceinline__ float shx(float v, int o, int lane) { return __builtin_bit_cast(float, __builtin_amdgcn_ds_bpermute((lane ^ o) << 2, __builtin_bit_cast(int, v))); }
; __device__ __forceinline__ float sigmoidf_(float z) { return __builtin_amdgcn_rcpf(1.0f + fast_exp2(-z * LOG2E)); }
; __device__ __forceinline__ void phase_hfin(const Params& P, int l) {
;     ...
;         for (int u = 0; u < 3; ++u) {
;             const long i = i0 + u * S; const bool ok = i < total; const long rh = (ok ? i : i0) >> 4; const int h = (int)(rh & 3); const long r = rh >> 2;
;             const size_t off = (size_t)r * 256 + h * 64 + sub * 4;
;             a[u] = *(const f32x4*)(od0 + off); b2[u] = *(const f32x4*)(od1 + off);
;             gw[u] = *(const u32x2*)(proj + (size_t)r * INW + PB_G + h * 64 + sub * 4);
;         }
; #pragma unroll
;         for (int u = 0; u < 3; ++u) {
;             const long i = i0 + u * S; if (i >= total) break;
;             const long rh = i >> 4; const int h = (int)(rh & 3); const long r = rh >> 2;
;             const f32x4 o = a[u] + b2[u];
;             float ss = (o.x * o.x + o.y * o.y) + (o.z * o.z + o.w * o.w);
;             ss += shx(ss, 1, lane); ss += shx(ss, 2, lane); ss += shx(ss, 4, lane); ss += shx(ss, 8, lane);
;             const float rs = 1.0f / sqrtf(ss * (1.0f / 64.0f) + RMS_EPS);
;             const float g0 = bflo(gw[u].x), g1 = bfhi(gw[u].x), g2 = bflo(gw[u].y), g3 = bfhi(gw[u].y);
;             u32x2 w; w.x = pk2(o.x * rs * gg.x * (g0 * sigmoidf_(g0)), o.y * rs * gg.y * (g1 * sigmoidf_(g1))); w.y = pk2(o.z * rs * gg.z * (g2 * sigmoidf_(g2)), o.w * rs * gg.w * (g3 * sigmoidf_(g3)));
;             *(u32x2*)(mix + (size_t)r * DM + 256 + h * 64 + sub * 4) = w;
	s_waitcnt vmcnt(17)
	v_add_f32_e32 v72, v20, v24
	v_add_f32_e32 v73, v21, v25
	v_add_f32_e32 v74, v22, v26
	v_add_f32_e32 v75, v23, v27
	v_lshlrev_b32_e32 v84, 16, v28
	v_and_b32_e32 v85, 0xffff0000, v28
	v_lshlrev_b32_e32 v86, 16, v29
	v_and_b32_e32 v87, 0xffff0000, v29
	v_mul_f32_e32 v76, v73, v73
	v_mul_f32_e32 v77, v75, v75
	v_fmac_f32_e32 v76, v72, v72
	v_fmac_f32_e32 v77, v74, v74
	v_add_f32_e32 v78, v76, v77
	ds_bpermute_b32 v76, v67, v78
	v_mul_f32_e32 v88, 0xbfb8aa3b, v84
	v_mul_f32_e32 v89, 0xbfb8aa3b, v85
	v_mul_f32_e32 v90, 0xbfb8aa3b, v86
	v_mul_f32_e32 v91, 0xbfb8aa3b, v87
	s_waitcnt lgkmcnt(0)
	v_add_f32_e32 v78, v78, v76
	ds_bpermute_b32 v76, v68, v78
	v_exp_f32_e32 v88, v88
	v_exp_f32_e32 v89, v89
	v_exp_f32_e32 v90, v90
	v_exp_f32_e32 v91, v91
	s_waitcnt lgkmcnt(0)
	v_add_f32_e32 v78, v78, v76
	ds_bpermute_b32 v76, v69, v78
	v_add_f32_e32 v88, 1.0, v88
	v_add_f32_e32 v89, 1.0, v89
	v_add_f32_e32 v90, 1.0, v90
	v_add_f32_e32 v91, 1.0, v91
	s_waitcnt lgkmcnt(0)
	v_add_f32_e32 v78, v78, v76
	ds_bpermute_b32 v76, v70, v78
	v_rcp_f32_e32 v88, v88
	v_rcp_f32_e32 v89, v89
	v_rcp_f32_e32 v90, v90
	v_rcp_f32_e32 v91, v91
	s_waitcnt lgkmcnt(0)
	v_add_f32_e32 v78, v78, v76
	v_mul_f32_e32 v88, v88, v84
	v_mul_f32_e32 v89, v89, v85
	v_mul_f32_e32 v90, v90, v86
	v_mul_f32_e32 v91, v91, v87
	v_fmamk_f32 v78, v78, 0x3c800000, v201
	v_mul_f32_e32 v76, 0x4f800000, v78
	v_cmp_gt_f32_e32 vcc, 0xf800000, v78
	s_nop 1
	v_cndmask_b32_e32 v78, v78, v76, vcc
	v_sqrt_f32_e32 v76, v78
	s_nop 0
	v_add_u32_e32 v79, -1, v76
	v_add_u32_e32 v80, 1, v76
	v_fma_f32 v81, -v79, v76, v78
	v_fma_f32 v82, -v80, v76, v78
	v_cmp_ge_f32_e64 s[42:43], 0, v81
	s_nop 1
	v_cndmask_b32_e64 v76, v76, v79, s[42:43]
	v_cmp_lt_f32_e64 s[42:43], 0, v82
	s_nop 1
	v_cndmask_b32_e64 v76, v76, v80, s[42:43]
	v_mul_f32_e32 v79, 0x37800000, v76
	v_cndmask_b32_e32 v76, v76, v79, vcc
	v_cmp_class_f32_e32 vcc, v78, v202
	s_nop 1
	v_cndmask_b32_e32 v78, v76, v78, vcc
	v_div_scale_f32 v76, s[42:43], v78, v78, 1.0
	v_rcp_f32_e32 v79, v76
	v_div_scale_f32 v80, vcc, 1.0, v78, 1.0
	v_fma_f32 v81, -v76, v79, 1.0
	v_fmac_f32_e32 v79, v81, v79
	v_mul_f32_e32 v81, v80, v79
	v_fma_f32 v82, -v76, v81, v80
	v_fmac_f32_e32 v81, v82, v79
	v_fma_f32 v76, -v76, v81, v80
	v_div_fmas_f32 v76, v76, v79, v81
	v_div_fixup_f32 v83, v76, v78, 1.0
	v_mul_f32_e32 v92, v72, v83
	v_mul_f32_e32 v92, v60, v92
	v_mul_f32_e32 v92, v88, v92
	v_mul_f32_e32 v93, v73, v83
	v_mul_f32_e32 v93, v61, v93
	v_mul_f32_e32 v93, v89, v93
	v_mul_f32_e32 v94, v74, v83
	v_mul_f32_e32 v94, v62, v94
	v_mul_f32_e32 v94, v90, v94
	v_mul_f32_e32 v95, v75, v83
	v_mul_f32_e32 v95, v63, v95
	v_mul_f32_e32 v95, v91, v95
	v_cvt_pk_bf16_f32 v96, v92, v93
	v_cvt_pk_bf16_f32 v97, v94, v95
	s_lshl_b32 s12, s101, 11
	s_add_u32 s8, s40, s12
	s_addc_u32 s9, s41, 0
	global_store_dwordx2 v65, v[96:97], s[8:9]
	s_mul_i32 s100, 8, 6
	s_add_u32 s100, s100, s101
	s_cmp_le_u32 s100, s15
	s_cselect_b32 s100, s100, s101
	s_lshl_b32 s12, s100, 10
	s_add_u32 s8, s46, s12
	s_addc_u32 s9, s47, 0
	global_load_dwordx4 v[20:23], v64, s[8:9]
	s_add_u32 s8, s48, s12
	s_addc_u32 s9, s49, 0
	global_load_dwordx4 v[24:27], v64, s[8:9]
	s_mul_i32 s12, s100, 0x1600
	s_add_u32 s8, s38, s12
	s_addc_u32 s9, s39, 0
	global_load_dwordx2 v[28:29], v65, s[8:9]
	s_add_u32 s101, s101, 8
	s_cmp_gt_u32 s101, s15
	s_cbranch_scc1 .Lhfu_exit
	s_waitcnt vmcnt(18)
	v_add_f32_e32 v72, v30, v34
	v_add_f32_e32 v73, v31, v35
	v_add_f32_e32 v74, v32, v36
	v_add_f32_e32 v75, v33, v37
	v_lshlrev_b32_e32 v84, 16, v38
	v_and_b32_e32 v85, 0xffff0000, v38
	v_lshlrev_b32_e32 v86, 16, v39
	v_and_b32_e32 v87, 0xffff0000, v39
	v_mul_f32_e32 v76, v73, v73
	v_mul_f32_e32 v77, v75, v75
	v_fmac_f32_e32 v76, v72, v72
	v_fmac_f32_e32 v77, v74, v74
	v_add_f32_e32 v78, v76, v77
	ds_bpermute_b32 v76, v67, v78
	v_mul_f32_e32 v88, 0xbfb8aa3b, v84
	v_mul_f32_e32 v89, 0xbfb8aa3b, v85
	v_mul_f32_e32 v90, 0xbfb8aa3b, v86
	v_mul_f32_e32 v91, 0xbfb8aa3b, v87
	s_waitcnt lgkmcnt(0)
	v_add_f32_e32 v78, v78, v76
	ds_bpermute_b32 v76, v68, v78
	v_exp_f32_e32 v88, v88
	v_exp_f32_e32 v89, v89
	v_exp_f32_e32 v90, v90
	v_exp_f32_e32 v91, v91
	s_waitcnt lgkmcnt(0)
	v_add_f32_e32 v78, v78, v76
	ds_bpermute_b32 v76, v69, v78
	v_add_f32_e32 v88, 1.0, v88
	v_add_f32_e32 v89, 1.0, v89
	v_add_f32_e32 v90, 1.0, v90
	v_add_f32_e32 v91, 1.0, v91
	s_waitcnt lgkmcnt(0)
	v_add_f32_e32 v78, v78, v76
	ds_bpermute_b32 v76, v70, v78
	v_rcp_f32_e32 v88, v88
	v_rcp_f32_e32 v89, v89
	v_rcp_f32_e32 v90, v90
	v_rcp_f32_e32 v91, v91
	s_waitcnt lgkmcnt(0)
	v_add_f32_e32 v78, v78, v76
	v_mul_f32_e32 v88, v88, v84
	v_mul_f32_e32 v89, v89, v85
	v_mul_f32_e32 v90, v90, v86
	v_mul_f32_e32 v91, v91, v87
	v_fmamk_f32 v78, v78, 0x3c800000, v201
	v_mul_f32_e32 v76, 0x4f800000, v78
	v_cmp_gt_f32_e32 vcc, 0xf800000, v78
	s_nop 1
	v_cndmask_b32_e32 v78, v78, v76, vcc
	v_sqrt_f32_e32 v76, v78
	s_nop 0
	v_add_u32_e32 v79, -1, v76
	v_add_u32_e32 v80, 1, v76
	v_fma_f32 v81, -v79, v76, v78
	v_fma_f32 v82, -v80, v76, v78
	v_cmp_ge_f32_e64 s[42:43], 0, v81
	s_nop 1
	v_cndmask_b32_e64 v76, v76, v79, s[42:43]
	v_cmp_lt_f32_e64 s[42:43], 0, v82
	s_nop 1
	v_cndmask_b32_e64 v76, v76, v80, s[42:43]
	v_mul_f32_e32 v79, 0x37800000, v76
	v_cndmask_b32_e32 v76, v76, v79, vcc
	v_cmp_class_f32_e32 vcc, v78, v202
	s_nop 1
	v_cndmask_b32_e32 v78, v76, v78, vcc
	v_div_scale_f32 v76, s[42:43], v78, v78, 1.0
	v_rcp_f32_e32 v79, v76
	v_div_scale_f32 v80, vcc, 1.0, v78, 1.0
	v_fma_f32 v81, -v76, v79, 1.0
	v_fmac_f32_e32 v79, v81, v79
	v_mul_f32_e32 v81, v80, v79
	v_fma_f32 v82, -v76, v81, v80
	v_fmac_f32_e32 v81, v82, v79
	v_fma_f32 v76, -v76, v81, v80
	v_div_fmas_f32 v76, v76, v79, v81
	v_div_fixup_f32 v83, v76, v78, 1.0
	v_mul_f32_e32 v92, v72, v83
	v_mul_f32_e32 v92, v60, v92
	v_mul_f32_e32 v92, v88, v92
	v_mul_f32_e32 v93, v73, v83
	v_mul_f32_e32 v93, v61, v93
	v_mul_f32_e32 v93, v89, v93
	v_mul_f32_e32 v94, v74, v83
	v_mul_f32_e32 v94, v62, v94
	v_mul_f32_e32 v94, v90, v94
	v_mul_f32_e32 v95, v75, v83
	v_mul_f32_e32 v95, v63, v95
	v_mul_f32_e32 v95, v91, v95
	v_cvt_pk_bf16_f32 v96, v92, v93
	v_cvt_pk_bf16_f32 v97, v94, v95
	s_lshl_b32 s12, s101, 11
	s_add_u32 s8, s40, s12
	s_addc_u32 s9, s41, 0
	global_store_dwordx2 v65, v[96:97], s[8:9]
	s_mul_i32 s100, 8, 6
	s_add_u32 s100, s100, s101
	s_cmp_le_u32 s100, s15
	s_cselect_b32 s100, s100, s101
	s_lshl_b32 s12, s100, 10
	s_add_u32 s8, s46, s12
	s_addc_u32 s9, s47, 0
	global_load_dwordx4 v[30:33], v64, s[8:9]
	s_add_u32 s8, s48, s12
	s_addc_u32 s9, s49, 0
	global_load_dwordx4 v[34:37], v64, s[8:9]
	s_mul_i32 s12, s100, 0x1600
	s_add_u32 s8, s38, s12
	s_addc_u32 s9, s39, 0
	global_load_dwordx2 v[38:39], v65, s[8:9]
	s_add_u32 s101, s101, 8
	s_cmp_gt_u32 s101, s15
	s_cbranch_scc1 .Lhfu_exit
; __device__ __forceinline__ unsigned pk2(float lo, float hi) { f32x2_t v = {lo, hi}; bf16x2_t b = __builtin_convertvector(v, bf16x2_t); return __builtin_bit_cast(unsigned, b); }
; __device__ __forceinline__ float shx(float v, int o, int lane) { return __builtin_bit_cast(float, __builtin_amdgcn_ds_bpermute((lane ^ o) << 2, __builtin_bit_cast(int, v))); }
; __device__ __forceinline__ float sigmoidf_(float z) { return __builtin_amdgcn_rcpf(1.0f + fast_exp2(-z * LOG2E)); }
; __device__ __forceinline__ void phase_hfin(const Params& P, int l) {
;     ...
;         for (int u = 0; u < 3; ++u) {
;             const long i = i0 + u * S; const bool ok = i < total; const long rh = (ok ? i : i0) >> 4; const int h = (int)(rh & 3); const long r = rh >> 2;
;             const size_t off = (size_t)r * 256 + h * 64 + sub * 4;
;             a[u] = *(const f32x4*)(od0 + off); b2[u] = *(const f32x4*)(od1 + off);
;             gw[u] = *(const u32x2*)(proj + (size_t)r * INW + PB_G + h * 64 + sub * 4);
;         }
; #pragma unroll
;         for (int u = 0; u < 3; ++u) {
;             const long i = i0 + u * S; if (i >= total) break;
;             const long rh = i >> 4; const int h = (int)(rh & 3); const long r = rh >> 2;
;             const f32x4 o = a[u] + b2[u];
;             float ss = (o.x * o.x + o.y * o.y) + (o.z * o.z + o.w * o.w);
;             ss += shx(ss, 1, lane); ss += shx(ss, 2, lane); ss += shx(ss, 4, lane); ss += shx(ss, 8, lane);
;             const float rs = 1.0f / sqrtf(ss * (1.0f / 64.0f) + RMS_EPS);
;             const float g0 = bflo(gw[u].x), g1 = bfhi(gw[u].x), g2 = bflo(gw[u].y), g3 = bfhi(gw[u].y);
;             u32x2 w; w.x = pk2(o.x * rs * gg.x * (g0 * sigmoidf_(g0)), o.y * rs * gg.y * (g1 * sigmoidf_(g1))); w.y = pk2(o.z * rs * gg.z * (g2 * sigmoidf_(g2)), o.w * rs * gg.w * (g3 * sigmoidf_(g3)));
;             *(u32x2*)(mix + (size_t)r * DM + 256 + h * 64 + sub * 4) = w;
	s_waitcnt vmcnt(19)
	v_add_f32_e32 v72, v40, v44
	v_add_f32_e32 v73, v41, v45
	v_add_f32_e32 v74, v42, v46
	v_add_f32_e32 v75, v43, v47
	v_lshlrev_b32_e32 v84, 16, v48
	v_and_b32_e32 v85, 0xffff0000, v48
	v_lshlrev_b32_e32 v86, 16, v49
	v_and_b32_e32 v87, 0xffff0000, v49
	v_mul_f32_e32 v76, v73, v73
	v_mul_f32_e32 v77, v75, v75
	v_fmac_f32_e32 v76, v72, v72
	v_fmac_f32_e32 v77, v74, v74
	v_add_f32_e32 v78, v76, v77
	ds_bpermute_b32 v76, v67, v78
	v_mul_f32_e32 v88, 0xbfb8aa3b, v84
	v_mul_f32_e32 v89, 0xbfb8aa3b, v85
	v_mul_f32_e32 v90, 0xbfb8aa3b, v86
	v_mul_f32_e32 v91, 0xbfb8aa3b, v87
	s_waitcnt lgkmcnt(0)
	v_add_f32_e32 v78, v78, v76
	ds_bpermute_b32 v76, v68, v78
	v_exp_f32_e32 v88, v88
	v_exp_f32_e32 v89, v89
	v_exp_f32_e32 v90, v90
	v_exp_f32_e32 v91, v91
	s_waitcnt lgkmcnt(0)
	v_add_f32_e32 v78, v78, v76
	ds_bpermute_b32 v76, v69, v78
	v_add_f32_e32 v88, 1.0, v88
	v_add_f32_e32 v89, 1.0, v89
	v_add_f32_e32 v90, 1.0, v90
	v_add_f32_e32 v91, 1.0, v91
	s_waitcnt lgkmcnt(0)
	v_add_f32_e32 v78, v78, v76
	ds_bpermute_b32 v76, v70, v78
	v_rcp_f32_e32 v88, v88
	v_rcp_f32_e32 v89, v89
	v_rcp_f32_e32 v90, v90
	v_rcp_f32_e32 v91, v91
	s_waitcnt lgkmcnt(0)
	v_add_f32_e32 v78, v78, v76
	v_mul_f32_e32 v88, v88, v84
	v_mul_f32_e32 v89, v89, v85
	v_mul_f32_e32 v90, v90, v86
	v_mul_f32_e32 v91, v91, v87
	v_fmamk_f32 v78, v78, 0x3c800000, v201
	v_mul_f32_e32 v76, 0x4f800000, v78
	v_cmp_gt_f32_e32 vcc, 0xf800000, v78
	s_nop 1
	v_cndmask_b32_e32 v78, v78, v76, vcc
	v_sqrt_f32_e32 v76, v78
	s_nop 0
	v_add_u32_e32 v79, -1, v76
	v_add_u32_e32 v80, 1, v76
	v_fma_f32 v81, -v79, v76, v78
	v_fma_f32 v82, -v80, v76, v78
	v_cmp_ge_f32_e64 s[42:43], 0, v81
	s_nop 1
	v_cndmask_b32_e64 v76, v76, v79, s[42:43]
	v_cmp_lt_f32_e64 s[42:43], 0, v82
	s_nop 1
	v_cndmask_b32_e64 v76, v76, v80, s[42:43]
	v_mul_f32_e32 v79, 0x37800000, v76
	v_cndmask_b32_e32 v76, v76, v79, vcc
	v_cmp_class_f32_e32 vcc, v78, v202
	s_nop 1
	v_cndmask_b32_e32 v78, v76, v78, vcc
	v_div_scale_f32 v76, s[42:43], v78, v78, 1.0
	v_rcp_f32_e32 v79, v76
	v_div_scale_f32 v80, vcc, 1.0, v78, 1.0
	v_fma_f32 v81, -v76, v79, 1.0
	v_fmac_f32_e32 v79, v81, v79
	v_mul_f32_e32 v81, v80, v79
	v_fma_f32 v82, -v76, v81, v80
	v_fmac_f32_e32 v81, v82, v79
	v_fma_f32 v76, -v76, v81, v80
	v_div_fmas_f32 v76, v76, v79, v81
	v_div_fixup_f32 v83, v76, v78, 1.0
	v_mul_f32_e32 v92, v72, v83
	v_mul_f32_e32 v92, v60, v92
	v_mul_f32_e32 v92, v88, v92
	v_mul_f32_e32 v93, v73, v83
	v_mul_f32_e32 v93, v61, v93
	v_mul_f32_e32 v93, v89, v93
	v_mul_f32_e32 v94, v74, v83
	v_mul_f32_e32 v94, v62, v94
	v_mul_f32_e32 v94, v90, v94
	v_mul_f32_e32 v95, v75, v83
	v_mul_f32_e32 v95, v63, v95
	v_mul_f32_e32 v95, v91, v95
	v_cvt_pk_bf16_f32 v96, v92, v93
	v_cvt_pk_bf16_f32 v97, v94, v95
	s_lshl_b32 s12, s101, 11
	s_add_u32 s8, s40, s12
	s_addc_u32 s9, s41, 0
	global_store_dwordx2 v65, v[96:97], s[8:9]
	s_mul_i32 s100, 8, 6
	s_add_u32 s100, s100, s101
	s_cmp_le_u32 s100, s15
	s_cselect_b32 s100, s100, s101
	s_lshl_b32 s12, s100, 10
	s_add_u32 s8, s46, s12
	s_addc_u32 s9, s47, 0
	global_load_dwordx4 v[40:43], v64, s[8:9]
	s_add_u32 s8, s48, s12
	s_addc_u32 s9, s49, 0
	global_load_dwordx4 v[44:47], v64, s[8:9]
	s_mul_i32 s12, s100, 0x1600
	s_add_u32 s8, s38, s12
	s_addc_u32 s9, s39, 0
	global_load_dwordx2 v[48:49], v65, s[8:9]
	s_add_u32 s101, s101, 8
	s_cmp_gt_u32 s101, s15
	s_cbranch_scc1 .Lhfu_exit
	s_waitcnt vmcnt(20)
	v_add_f32_e32 v72, v50, v54
	v_add_f32_e32 v73, v51, v55
	v_add_f32_e32 v74, v52, v56
	v_add_f32_e32 v75, v53, v57
	v_lshlrev_b32_e32 v84, 16, v58
	v_and_b32_e32 v85, 0xffff0000, v58
	v_lshlrev_b32_e32 v86, 16, v59
	v_and_b32_e32 v87, 0xffff0000, v59
	v_mul_f32_e32 v76, v73, v73
	v_mul_f32_e32 v77, v75, v75
	v_fmac_f32_e32 v76, v72, v72
	v_fmac_f32_e32 v77, v74, v74
	v_add_f32_e32 v78, v76, v77
	ds_bpermute_b32 v76, v67, v78
	v_mul_f32_e32 v88, 0xbfb8aa3b, v84
	v_mul_f32_e32 v89, 0xbfb8aa3b, v85
	v_mul_f32_e32 v90, 0xbfb8aa3b, v86
	v_mul_f32_e32 v91, 0xbfb8aa3b, v87
	s_waitcnt lgkmcnt(0)
	v_add_f32_e32 v78, v78, v76
	ds_bpermute_b32 v76, v68, v78
	v_exp_f32_e32 v88, v88
	v_exp_f32_e32 v89, v89
	v_exp_f32_e32 v90, v90
	v_exp_f32_e32 v91, v91
	s_waitcnt lgkmcnt(0)
	v_add_f32_e32 v78, v78, v76
	ds_bpermute_b32 v76, v69, v78
	v_add_f32_e32 v88, 1.0, v88
	v_add_f32_e32 v89, 1.0, v89
	v_add_f32_e32 v90, 1.0, v90
	v_add_f32_e32 v91, 1.0, v91
	s_waitcnt lgkmcnt(0)
	v_add_f32_e32 v78, v78, v76
	ds_bpermute_b32 v76, v70, v78
	v_rcp_f32_e32 v88, v88
	v_rcp_f32_e32 v89, v89
	v_rcp_f32_e32 v90, v90
	v_rcp_f32_e32 v91, v91
	s_waitcnt lgkmcnt(0)
	v_add_f32_e32 v78, v78, v76
	v_mul_f32_e32 v88, v88, v84
	v_mul_f32_e32 v89, v89, v85
	v_mul_f32_e32 v90, v90, v86
	v_mul_f32_e32 v91, v91, v87
	v_fmamk_f32 v78, v78, 0x3c800000, v201
	v_mul_f32_e32 v76, 0x4f800000, v78
	v_cmp_gt_f32_e32 vcc, 0xf800000, v78
	s_nop 1
	v_cndmask_b32_e32 v78, v78, v76, vcc
	v_sqrt_f32_e32 v76, v78
	s_nop 0
	v_add_u32_e32 v79, -1, v76
	v_add_u32_e32 v80, 1, v76
	v_fma_f32 v81, -v79, v76, v78
	v_fma_f32 v82, -v80, v76, v78
	v_cmp_ge_f32_e64 s[42:43], 0, v81
	s_nop 1
	v_cndmask_b32_e64 v76, v76, v79, s[42:43]
	v_cmp_lt_f32_e64 s[42:43], 0, v82
	s_nop 1
	v_cndmask_b32_e64 v76, v76, v80, s[42:43]
	v_mul_f32_e32 v79, 0x37800000, v76
	v_cndmask_b32_e32 v76, v76, v79, vcc
	v_cmp_class_f32_e32 vcc, v78, v202
	s_nop 1
	v_cndmask_b32_e32 v78, v76, v78, vcc
	v_div_scale_f32 v76, s[42:43], v78, v78, 1.0
	v_rcp_f32_e32 v79, v76
	v_div_scale_f32 v80, vcc, 1.0, v78, 1.0
	v_fma_f32 v81, -v76, v79, 1.0
	v_fmac_f32_e32 v79, v81, v79
	v_mul_f32_e32 v81, v80, v79
	v_fma_f32 v82, -v76, v81, v80
	v_fmac_f32_e32 v81, v82, v79
	v_fma_f32 v76, -v76, v81, v80
	v_div_fmas_f32 v76, v76, v79, v81
	v_div_fixup_f32 v83, v76, v78, 1.0
	v_mul_f32_e32 v92, v72, v83
	v_mul_f32_e32 v92, v60, v92
	v_mul_f32_e32 v92, v88, v92
	v_mul_f32_e32 v93, v73, v83
	v_mul_f32_e32 v93, v61, v93
	v_mul_f32_e32 v93, v89, v93
	v_mul_f32_e32 v94, v74, v83
	v_mul_f32_e32 v94, v62, v94
	v_mul_f32_e32 v94, v90, v94
	v_mul_f32_e32 v95, v75, v83
	v_mul_f32_e32 v95, v63, v95
	v_mul_f32_e32 v95, v91, v95
	v_cvt_pk_bf16_f32 v96, v92, v93
	v_cvt_pk_bf16_f32 v97, v94, v95
	s_lshl_b32 s12, s101, 11
	s_add_u32 s8, s40, s12
	s_addc_u32 s9, s41, 0
	global_store_dwordx2 v65, v[96:97], s[8:9]
	s_mul_i32 s100, 8, 6
	s_add_u32 s100, s100, s101
	s_cmp_le_u32 s100, s15
	s_cselect_b32 s100, s100, s101
	s_lshl_b32 s12, s100, 10
	s_add_u32 s8, s46, s12
	s_addc_u32 s9, s47, 0
	global_load_dwordx4 v[50:53], v64, s[8:9]
	s_add_u32 s8, s48, s12
	s_addc_u32 s9, s49, 0
	global_load_dwordx4 v[54:57], v64, s[8:9]
	s_mul_i32 s12, s100, 0x1600
	s_add_u32 s8, s38, s12
	s_addc_u32 s9, s39, 0
	global_load_dwordx2 v[58:59], v65, s[8:9]
	s_add_u32 s101, s101, 8
	s_cmp_gt_u32 s101, s15
	s_cbranch_scc1 .Lhfu_exit
; __device__ __forceinline__ unsigned pk2(float lo, float hi) { f32x2_t v = {lo, hi}; bf16x2_t b = __builtin_convertvector(v, bf16x2_t); return __builtin_bit_cast(unsigned, b); }
; __device__ __forceinline__ float shx(float v, int o, int lane) { return __builtin_bit_cast(float, __builtin_amdgcn_ds_bpermute((lane ^ o) << 2, __builtin_bit_cast(int, v))); }
; __device__ __forceinline__ float sigmoidf_(float z) { return __builtin_amdgcn_rcpf(1.0f + fast_exp2(-z * LOG2E)); }
; __device__ __forceinline__ void phase_hfin(const Params& P, int l) {
;     ...
;         for (int u = 0; u < 3; ++u) {
;             const long i = i0 + u * S; const bool ok = i < total; const long rh = (ok ? i : i0) >> 4; const int h = (int)(rh & 3); const long r = rh >> 2;
;             const size_t off = (size_t)r * 256 + h * 64 + sub * 4;
;             a[u] = *(const f32x4*)(od0 + off); b2[u] = *(const f32x4*)(od1 + off);
;             gw[u] = *(const u32x2*)(proj + (size_t)r * INW + PB_G + h * 64 + sub * 4);
;         }
; #pragma unroll
;         for (int u = 0; u < 3; ++u) {
;             const long i = i0 + u * S; if (i >= total) break;
;             const long rh = i >> 4; const int h = (int)(rh & 3); const long r = rh >> 2;
;             const f32x4 o = a[u] + b2[u];
;             float ss = (o.x * o.x + o.y * o.y) + (o.z * o.z + o.w * o.w);
;             ss += shx(ss, 1, lane); ss += shx(ss, 2, lane); ss += shx(ss, 4, lane); ss += shx(ss, 8, lane);
;             const float rs = 1.0f / sqrtf(ss * (1.0f / 64.0f) + RMS_EPS);
;             const float g0 = bflo(gw[u].x), g1 = bfhi(gw[u].x), g2 = bflo(gw[u].y), g3 = bfhi(gw[u].y);
;             u32x2 w; w.x = pk2(o.x * rs * gg.x * (g0 * sigmoidf_(g0)), o.y * rs * gg.y * (g1 * sigmoidf_(g1))); w.y = pk2(o.z * rs * gg.z * (g2 * sigmoidf_(g2)), o.w * rs * gg.w * (g3 * sigmoidf_(g3)));
;             *(u32x2*)(mix + (size_t)r * DM + 256 + h * 64 + sub * 4) = w;
.Lhfu_loop:
	s_waitcnt vmcnt(20)
	v_add_f32_e32 v72, v0, v4
	v_add_f32_e32 v73, v1, v5
	v_add_f32_e32 v74, v2, v6
	v_add_f32_e32 v75, v3, v7
	v_lshlrev_b32_e32 v84, 16, v8
	v_and_b32_e32 v85, 0xffff0000, v8
	v_lshlrev_b32_e32 v86, 16, v9
	v_and_b32_e32 v87, 0xffff0000, v9
	v_mul_f32_e32 v76, v73, v73
	v_mul_f32_e32 v77, v75, v75
	v_fmac_f32_e32 v76, v72, v72
	v_fmac_f32_e32 v77, v74, v74
	v_add_f32_e32 v78, v76, v77
	ds_bpermute_b32 v76, v67, v78
	v_mul_f32_e32 v88, 0xbfb8aa3b, v84
	v_mul_f32_e32 v89, 0xbfb8aa3b, v85
	v_mul_f32_e32 v90, 0xbfb8aa3b, v86
	v_mul_f32_e32 v91, 0xbfb8aa3b, v87
	s_waitcnt lgkmcnt(0)
	v_add_f32_e32 v78, v78, v76
	ds_bpermute_b32 v76, v68, v78
	v_exp_f32_e32 v88, v88
	v_exp_f32_e32 v89, v89
	v_exp_f32_e32 v90, v90
	v_exp_f32_e32 v91, v91
	s_waitcnt lgkmcnt(0)
	v_add_f32_e32 v78, v78, v76
	ds_bpermute_b32 v76, v69, v78
	v_add_f32_e32 v88, 1.0, v88
	v_add_f32_e32 v89, 1.0, v89
	v_add_f32_e32 v90, 1.0, v90
	v_add_f32_e32 v91, 1.0, v91
	s_waitcnt lgkmcnt(0)
	v_add_f32_e32 v78, v78, v76
	ds_bpermute_b32 v76, v70, v78
	v_rcp_f32_e32 v88, v88
	v_rcp_f32_e32 v89, v89
	v_rcp_f32_e32 v90, v90
	v_rcp_f32_e32 v91, v91
	s_waitcnt lgkmcnt(0)
	v_add_f32_e32 v78, v78, v76
	v_mul_f32_e32 v88, v88, v84
	v_mul_f32_e32 v89, v89, v85
	v_mul_f32_e32 v90, v90, v86
	v_mul_f32_e32 v91, v91, v87
	v_fmamk_f32 v78, v78, 0x3c800000, v201
	v_mul_f32_e32 v76, 0x4f800000, v78
	v_cmp_gt_f32_e32 vcc, 0xf800000, v78
	s_nop 1
	v_cndmask_b32_e32 v78, v78, v76, vcc
	v_sqrt_f32_e32 v76, v78
	s_nop 0
	v_add_u32_e32 v79, -1, v76
	v_add_u32_e32 v80, 1, v76
	v_fma_f32 v81, -v79, v76, v78
	v_fma_f32 v82, -v80, v76, v78
	v_cmp_ge_f32_e64 s[42:43], 0, v81
	s_nop 1
	v_cndmask_b32_e64 v76, v76, v79, s[42:43]
	v_cmp_lt_f32_e64 s[42:43], 0, v82
	s_nop 1
	v_cndmask_b32_e64 v76, v76, v80, s[42:43]
	v_mul_f32_e32 v79, 0x37800000, v76
	v_cndmask_b32_e32 v76, v76, v79, vcc
	v_cmp_class_f32_e32 vcc, v78, v202
	s_nop 1
	v_cndmask_b32_e32 v78, v76, v78, vcc
	v_div_scale_f32 v76, s[42:43], v78, v78, 1.0
	v_rcp_f32_e32 v79, v76
	v_div_scale_f32 v80, vcc, 1.0, v78, 1.0
	v_fma_f32 v81, -v76, v79, 1.0
	v_fmac_f32_e32 v79, v81, v79
	v_mul_f32_e32 v81, v80, v79
	v_fma_f32 v82, -v76, v81, v80
	v_fmac_f32_e32 v81, v82, v79
	v_fma_f32 v76, -v76, v81, v80
	v_div_fmas_f32 v76, v76, v79, v81
	v_div_fixup_f32 v83, v76, v78, 1.0
	v_mul_f32_e32 v92, v72, v83
	v_mul_f32_e32 v92, v60, v92
	v_mul_f32_e32 v92, v88, v92
	v_mul_f32_e32 v93, v73, v83
	v_mul_f32_e32 v93, v61, v93
	v_mul_f32_e32 v93, v89, v93
	v_mul_f32_e32 v94, v74, v83
	v_mul_f32_e32 v94, v62, v94
	v_mul_f32_e32 v94, v90, v94
	v_mul_f32_e32 v95, v75, v83
	v_mul_f32_e32 v95, v63, v95
	v_mul_f32_e32 v95, v91, v95
	v_cvt_pk_bf16_f32 v96, v92, v93
	v_cvt_pk_bf16_f32 v97, v94, v95
	s_lshl_b32 s12, s101, 11
	s_add_u32 s8, s40, s12
	s_addc_u32 s9, s41, 0
	global_store_dwordx2 v65, v[96:97], s[8:9]
	s_mul_i32 s100, 8, 6
	s_add_u32 s100, s100, s101
	s_cmp_le_u32 s100, s15
	s_cselect_b32 s100, s100, s101
	s_lshl_b32 s12, s100, 10
	s_add_u32 s8, s46, s12
	s_addc_u32 s9, s47, 0
	global_load_dwordx4 v[0:3], v64, s[8:9]
	s_add_u32 s8, s48, s12
	s_addc_u32 s9, s49, 0
	global_load_dwordx4 v[4:7], v64, s[8:9]
	s_mul_i32 s12, s100, 0x1600
	s_add_u32 s8, s38, s12
	s_addc_u32 s9, s39, 0
	global_load_dwordx2 v[8:9], v65, s[8:9]
	s_add_u32 s101, s101, 8
	s_cmp_gt_u32 s101, s15
	s_cbranch_scc1 .Lhfu_exit
	s_waitcnt vmcnt(20)
	v_add_f32_e32 v72, v10, v14
	v_add_f32_e32 v73, v11, v15
	v_add_f32_e32 v74, v12, v16
	v_add_f32_e32 v75, v13, v17
	v_lshlrev_b32_e32 v84, 16, v18
	v_and_b32_e32 v85, 0xffff0000, v18
	v_lshlrev_b32_e32 v86, 16, v19
	v_and_b32_e32 v87, 0xffff0000, v19
	v_mul_f32_e32 v76, v73, v73
	v_mul_f32_e32 v77, v75, v75
	v_fmac_f32_e32 v76, v72, v72
	v_fmac_f32_e32 v77, v74, v74
	v_add_f32_e32 v78, v76, v77
	ds_bpermute_b32 v76, v67, v78
	v_mul_f32_e32 v88, 0xbfb8aa3b, v84
	v_mul_f32_e32 v89, 0xbfb8aa3b, v85
	v_mul_f32_e32 v90, 0xbfb8aa3b, v86
	v_mul_f32_e32 v91, 0xbfb8aa3b, v87
	s_waitcnt lgkmcnt(0)
	v_add_f32_e32 v78, v78, v76
	ds_bpermute_b32 v76, v68, v78
	v_exp_f32_e32 v88, v88
	v_exp_f32_e32 v89, v89
	v_exp_f32_e32 v90, v90
	v_exp_f32_e32 v91, v91
	s_waitcnt lgkmcnt(0)
	v_add_f32_e32 v78, v78, v76
	ds_bpermute_b32 v76, v69, v78
	v_add_f32_e32 v88, 1.0, v88
	v_add_f32_e32 v89, 1.0, v89
	v_add_f32_e32 v90, 1.0, v90
	v_add_f32_e32 v91, 1.0, v91
	s_waitcnt lgkmcnt(0)
	v_add_f32_e32 v78, v78, v76
	ds_bpermute_b32 v76, v70, v78
	v_rcp_f32_e32 v88, v88
	v_rcp_f32_e32 v89, v89
	v_rcp_f32_e32 v90, v90
	v_rcp_f32_e32 v91, v91
	s_waitcnt lgkmcnt(0)
	v_add_f32_e32 v78, v78, v76
	v_mul_f32_e32 v88, v88, v84
	v_mul_f32_e32 v89, v89, v85
	v_mul_f32_e32 v90, v90, v86
	v_mul_f32_e32 v91, v91, v87
	v_fmamk_f32 v78, v78, 0x3c800000, v201
	v_mul_f32_e32 v76, 0x4f800000, v78
	v_cmp_gt_f32_e32 vcc, 0xf800000, v78
	s_nop 1
	v_cndmask_b32_e32 v78, v78, v76, vcc
	v_sqrt_f32_e32 v76, v78
	s_nop 0
	v_add_u32_e32 v79, -1, v76
	v_add_u32_e32 v80, 1, v76
	v_fma_f32 v81, -v79, v76, v78
	v_fma_f32 v82, -v80, v76, v78
	v_cmp_ge_f32_e64 s[42:43], 0, v81
	s_nop 1
	v_cndmask_b32_e64 v76, v76, v79, s[42:43]
	v_cmp_lt_f32_e64 s[42:43], 0, v82
	s_nop 1
	v_cndmask_b32_e64 v76, v76, v80, s[42:43]
	v_mul_f32_e32 v79, 0x37800000, v76
	v_cndmask_b32_e32 v76, v76, v79, vcc
	v_cmp_class_f32_e32 vcc, v78, v202
	s_nop 1
	v_cndmask_b32_e32 v78, v76, v78, vcc
	v_div_scale_f32 v76, s[42:43], v78, v78, 1.0
	v_rcp_f32_e32 v79, v76
	v_div_scale_f32 v80, vcc, 1.0, v78, 1.0
	v_fma_f32 v81, -v76, v79, 1.0
	v_fmac_f32_e32 v79, v81, v79
	v_mul_f32_e32 v81, v80, v79
	v_fma_f32 v82, -v76, v81, v80
	v_fmac_f32_e32 v81, v82, v79
	v_fma_f32 v76, -v76, v81, v80
	v_div_fmas_f32 v76, v76, v79, v81
	v_div_fixup_f32 v83, v76, v78, 1.0
	v_mul_f32_e32 v92, v72, v83
	v_mul_f32_e32 v92, v60, v92
	v_mul_f32_e32 v92, v88, v92
	v_mul_f32_e32 v93, v73, v83
	v_mul_f32_e32 v93, v61, v93
	v_mul_f32_e32 v93, v89, v93
	v_mul_f32_e32 v94, v74, v83
	v_mul_f32_e32 v94, v62, v94
	v_mul_f32_e32 v94, v90, v94
	v_mul_f32_e32 v95, v75, v83
	v_mul_f32_e32 v95, v63, v95
	v_mul_f32_e32 v95, v91, v95
	v_cvt_pk_bf16_f32 v96, v92, v93
	v_cvt_pk_bf16_f32 v97, v94, v95
	s_lshl_b32 s12, s101, 11
	s_add_u32 s8, s40, s12
	s_addc_u32 s9, s41, 0
	global_store_dwordx2 v65, v[96:97], s[8:9]
	s_mul_i32 s100, 8, 6
	s_add_u32 s100, s100, s101
	s_cmp_le_u32 s100, s15
	s_cselect_b32 s100, s100, s101
	s_lshl_b32 s12, s100, 10
	s_add_u32 s8, s46, s12
	s_addc_u32 s9, s47, 0
	global_load_dwordx4 v[10:13], v64, s[8:9]
	s_add_u32 s8, s48, s12
	s_addc_u32 s9, s49, 0
	global_load_dwordx4 v[14:17], v64, s[8:9]
	s_mul_i32 s12, s100, 0x1600
	s_add_u32 s8, s38, s12
	s_addc_u32 s9, s39, 0
	global_load_dwordx2 v[18:19], v65, s[8:9]
	s_add_u32 s101, s101, 8
	s_cmp_gt_u32 s101, s15
	s_cbranch_scc1 .Lhfu_exit
; __device__ __forceinline__ unsigned pk2(float lo, float hi) { f32x2_t v = {lo, hi}; bf16x2_t b = __builtin_convertvector(v, bf16x2_t); return __builtin_bit_cast(unsigned, b); }
; __device__ __forceinline__ float shx(float v, int o, int lane) { return __builtin_bit_cast(float, __builtin_amdgcn_ds_bpermute((lane ^ o) << 2, __builtin_bit_cast(int, v))); }
; __device__ __forceinline__ float sigmoidf_(float z) { return __builtin_amdgcn_rcpf(1.0f + fast_exp2(-z * LOG2E)); }
; __device__ __forceinline__ void phase_hfin(const Params& P, int l) {
;     ...
;         for (int u = 0; u < 3; ++u) {
;             const long i = i0 + u * S; const bool ok = i < total; const long rh = (ok ? i : i0) >> 4; const int h = (int)(rh & 3); const long r = rh >> 2;
;             const size_t off = (size_t)r * 256 + h * 64 + sub * 4;
;             a[u] = *(const f32x4*)(od0 + off); b2[u] = *(const f32x4*)(od1 + off);
;             gw[u] = *(const u32x2*)(proj + (size_t)r * INW + PB_G + h * 64 + sub * 4);
;         }
; #pragma unroll
;         for (int u = 0; u < 3; ++u) {
;             const long i = i0 + u * S; if (i >= total) break;
;             const long rh = i >> 4; const int h = (int)(rh & 3); const long r = rh >> 2;
;             const f32x4 o = a[u] + b2[u];
;             float ss = (o.x * o.x + o.y * o.y) + (o.z * o.z + o.w * o.w);
;             ss += shx(ss, 1, lane); ss += shx(ss, 2, lane); ss += shx(ss, 4, lane); ss += shx(ss, 8, lane);
;             const float rs = 1.0f / sqrtf(ss * (1.0f / 64.0f) + RMS_EPS);
;             const float g0 = bflo(gw[u].x), g1 = bfhi(gw[u].x), g2 = bflo(gw[u].y), g3 = bfhi(gw[u].y);
;             u32x2 w; w.x = pk2(o.x * rs * gg.x * (g0 * sigmoidf_(g0)), o.y * rs * gg.y * (g1 * sigmoidf_(g1))); w.y = pk2(o.z * rs * gg.z * (g2 * sigmoidf_(g2)), o.w * rs * gg.w * (g3 * sigmoidf_(g3)));
;             *(u32x2*)(mix + (size_t)r * DM + 256 + h * 64 + sub * 4) = w;
	s_waitcnt vmcnt(20)
	v_add_f32_e32 v72, v20, v24
	v_add_f32_e32 v73, v21, v25
	v_add_f32_e32 v74, v22, v26
	v_add_f32_e32 v75, v23, v27
	v_lshlrev_b32_e32 v84, 16, v28
	v_and_b32_e32 v85, 0xffff0000, v28
	v_lshlrev_b32_e32 v86, 16, v29
	v_and_b32_e32 v87, 0xffff0000, v29
	v_mul_f32_e32 v76, v73, v73
	v_mul_f32_e32 v77, v75, v75
	v_fmac_f32_e32 v76, v72, v72
	v_fmac_f32_e32 v77, v74, v74
	v_add_f32_e32 v78, v76, v77
	ds_bpermute_b32 v76, v67, v78
	v_mul_f32_e32 v88, 0xbfb8aa3b, v84
	v_mul_f32_e32 v89, 0xbfb8aa3b, v85
	v_mul_f32_e32 v90, 0xbfb8aa3b, v86
	v_mul_f32_e32 v91, 0xbfb8aa3b, v87
	s_waitcnt lgkmcnt(0)
	v_add_f32_e32 v78, v78, v76
	ds_bpermute_b32 v76, v68, v78
	v_exp_f32_e32 v88, v88
	v_exp_f32_e32 v89, v89
	v_exp_f32_e32 v90, v90
	v_exp_f32_e32 v91, v91
	s_waitcnt lgkmcnt(0)
	v_add_f32_e32 v78, v78, v76
	ds_bpermute_b32 v76, v69, v78
	v_add_f32_e32 v88, 1.0, v88
	v_add_f32_e32 v89, 1.0, v89
	v_add_f32_e32 v90, 1.0, v90
	v_add_f32_e32 v91, 1.0, v91
	s_waitcnt lgkmcnt(0)
	v_add_f32_e32 v78, v78, v76
	ds_bpermute_b32 v76, v70, v78
	v_rcp_f32_e32 v88, v88
	v_rcp_f32_e32 v89, v89
	v_rcp_f32_e32 v90, v90
	v_rcp_f32_e32 v91, v91
	s_waitcnt lgkmcnt(0)
	v_add_f32_e32 v78, v78, v76
	v_mul_f32_e32 v88, v88, v84
	v_mul_f32_e32 v89, v89, v85
	v_mul_f32_e32 v90, v90, v86
	v_mul_f32_e32 v91, v91, v87
	v_fmamk_f32 v78, v78, 0x3c800000, v201
	v_mul_f32_e32 v76, 0x4f800000, v78
	v_cmp_gt_f32_e32 vcc, 0xf800000, v78
	s_nop 1
	v_cndmask_b32_e32 v78, v78, v76, vcc
	v_sqrt_f32_e32 v76, v78
	s_nop 0
	v_add_u32_e32 v79, -1, v76
	v_add_u32_e32 v80, 1, v76
	v_fma_f32 v81, -v79, v76, v78
	v_fma_f32 v82, -v80, v76, v78
	v_cmp_ge_f32_e64 s[42:43], 0, v81
	s_nop 1
	v_cndmask_b32_e64 v76, v76, v79, s[42:43]
	v_cmp_lt_f32_e64 s[42:43], 0, v82
	s_nop 1
	v_cndmask_b32_e64 v76, v76, v80, s[42:43]
	v_mul_f32_e32 v79, 0x37800000, v76
	v_cndmask_b32_e32 v76, v76, v79, vcc
	v_cmp_class_f32_e32 vcc, v78, v202
	s_nop 1
	v_cndmask_b32_e32 v78, v76, v78, vcc
	v_div_scale_f32 v76, s[42:43], v78, v78, 1.0
	v_rcp_f32_e32 v79, v76
	v_div_scale_f32 v80, vcc, 1.0, v78, 1.0
	v_fma_f32 v81, -v76, v79, 1.0
	v_fmac_f32_e32 v79, v81, v79
	v_mul_f32_e32 v81, v80, v79
	v_fma_f32 v82, -v76, v81, v80
	v_fmac_f32_e32 v81, v82, v79
	v_fma_f32 v76, -v76, v81, v80
	v_div_fmas_f32 v76, v76, v79, v81
	v_div_fixup_f32 v83, v76, v78, 1.0
	v_mul_f32_e32 v92, v72, v83
	v_mul_f32_e32 v92, v60, v92
	v_mul_f32_e32 v92, v88, v92
	v_mul_f32_e32 v93, v73, v83
	v_mul_f32_e32 v93, v61, v93
	v_mul_f32_e32 v93, v89, v93
	v_mul_f32_e32 v94, v74, v83
	v_mul_f32_e32 v94, v62, v94
	v_mul_f32_e32 v94, v90, v94
	v_mul_f32_e32 v95, v75, v83
	v_mul_f32_e32 v95, v63, v95
	v_mul_f32_e32 v95, v91, v95
	v_cvt_pk_bf16_f32 v96, v92, v93
	v_cvt_pk_bf16_f32 v97, v94, v95
	s_lshl_b32 s12, s101, 11
	s_add_u32 s8, s40, s12
	s_addc_u32 s9, s41, 0
	global_store_dwordx2 v65, v[96:97], s[8:9]
	s_mul_i32 s100, 8, 6
	s_add_u32 s100, s100, s101
	s_cmp_le_u32 s100, s15
	s_cselect_b32 s100, s100, s101
	s_lshl_b32 s12, s100, 10
	s_add_u32 s8, s46, s12
	s_addc_u32 s9, s47, 0
	global_load_dwordx4 v[20:23], v64, s[8:9]
	s_add_u32 s8, s48, s12
	s_addc_u32 s9, s49, 0
	global_load_dwordx4 v[24:27], v64, s[8:9]
	s_mul_i32 s12, s100, 0x1600
	s_add_u32 s8, s38, s12
	s_addc_u32 s9, s39, 0
	global_load_dwordx2 v[28:29], v65, s[8:9]
	s_add_u32 s101, s101, 8
	s_cmp_gt_u32 s101, s15
	s_cbranch_scc1 .Lhfu_exit
	s_waitcnt vmcnt(20)
	v_add_f32_e32 v72, v30, v34
	v_add_f32_e32 v73, v31, v35
	v_add_f32_e32 v74, v32, v36
	v_add_f32_e32 v75, v33, v37
	v_lshlrev_b32_e32 v84, 16, v38
	v_and_b32_e32 v85, 0xffff0000, v38
	v_lshlrev_b32_e32 v86, 16, v39
	v_and_b32_e32 v87, 0xffff0000, v39
	v_mul_f32_e32 v76, v73, v73
	v_mul_f32_e32 v77, v75, v75
	v_fmac_f32_e32 v76, v72, v72
	v_fmac_f32_e32 v77, v74, v74
	v_add_f32_e32 v78, v76, v77
	ds_bpermute_b32 v76, v67, v78
	v_mul_f32_e32 v88, 0xbfb8aa3b, v84
	v_mul_f32_e32 v89, 0xbfb8aa3b, v85
	v_mul_f32_e32 v90, 0xbfb8aa3b, v86
	v_mul_f32_e32 v91, 0xbfb8aa3b, v87
	s_waitcnt lgkmcnt(0)
	v_add_f32_e32 v78, v78, v76
	ds_bpermute_b32 v76, v68, v78
	v_exp_f32_e32 v88, v88
	v_exp_f32_e32 v89, v89
	v_exp_f32_e32 v90, v90
	v_exp_f32_e32 v91, v91
	s_waitcnt lgkmcnt(0)
	v_add_f32_e32 v78, v78, v76
	ds_bpermute_b32 v76, v69, v78
	v_add_f32_e32 v88, 1.0, v88
	v_add_f32_e32 v89, 1.0, v89
	v_add_f32_e32 v90, 1.0, v90
	v_add_f32_e32 v91, 1.0, v91
	s_waitcnt lgkmcnt(0)
	v_add_f32_e32 v78, v78, v76
	ds_bpermute_b32 v76, v70, v78
	v_rcp_f32_e32 v88, v88
	v_rcp_f32_e32 v89, v89
	v_rcp_f32_e32 v90, v90
	v_rcp_f32_e32 v91, v91
	s_waitcnt lgkmcnt(0)
	v_add_f32_e32 v78, v78, v76
	v_mul_f32_e32 v88, v88, v84
	v_mul_f32_e32 v89, v89, v85
	v_mul_f32_e32 v90, v90, v86
	v_mul_f32_e32 v91, v91, v87
	v_fmamk_f32 v78, v78, 0x3c800000, v201
	v_mul_f32_e32 v76, 0x4f800000, v78
	v_cmp_gt_f32_e32 vcc, 0xf800000, v78
	s_nop 1
	v_cndmask_b32_e32 v78, v78, v76, vcc
	v_sqrt_f32_e32 v76, v78
	s_nop 0
	v_add_u32_e32 v79, -1, v76
	v_add_u32_e32 v80, 1, v76
	v_fma_f32 v81, -v79, v76, v78
	v_fma_f32 v82, -v80, v76, v78
	v_cmp_ge_f32_e64 s[42:43], 0, v81
	s_nop 1
	v_cndmask_b32_e64 v76, v76, v79, s[42:43]
	v_cmp_lt_f32_e64 s[42:43], 0, v82
	s_nop 1
	v_cndmask_b32_e64 v76, v76, v80, s[42:43]
	v_mul_f32_e32 v79, 0x37800000, v76
	v_cndmask_b32_e32 v76, v76, v79, vcc
	v_cmp_class_f32_e32 vcc, v78, v202
	s_nop 1
	v_cndmask_b32_e32 v78, v76, v78, vcc
	v_div_scale_f32 v76, s[42:43], v78, v78, 1.0
	v_rcp_f32_e32 v79, v76
	v_div_scale_f32 v80, vcc, 1.0, v78, 1.0
	v_fma_f32 v81, -v76, v79, 1.0
	v_fmac_f32_e32 v79, v81, v79
	v_mul_f32_e32 v81, v80, v79
	v_fma_f32 v82, -v76, v81, v80
	v_fmac_f32_e32 v81, v82, v79
	v_fma_f32 v76, -v76, v81, v80
	v_div_fmas_f32 v76, v76, v79, v81
	v_div_fixup_f32 v83, v76, v78, 1.0
	v_mul_f32_e32 v92, v72, v83
	v_mul_f32_e32 v92, v60, v92
	v_mul_f32_e32 v92, v88, v92
	v_mul_f32_e32 v93, v73, v83
	v_mul_f32_e32 v93, v61, v93
	v_mul_f32_e32 v93, v89, v93
	v_mul_f32_e32 v94, v74, v83
	v_mul_f32_e32 v94, v62, v94
	v_mul_f32_e32 v94, v90, v94
	v_mul_f32_e32 v95, v75, v83
	v_mul_f32_e32 v95, v63, v95
	v_mul_f32_e32 v95, v91, v95
	v_cvt_pk_bf16_f32 v96, v92, v93
	v_cvt_pk_bf16_f32 v97, v94, v95
	s_lshl_b32 s12, s101, 11
	s_add_u32 s8, s40, s12
	s_addc_u32 s9, s41, 0
	global_store_dwordx2 v65, v[96:97], s[8:9]
	s_mul_i32 s100, 8, 6
	s_add_u32 s100, s100, s101
	s_cmp_le_u32 s100, s15
	s_cselect_b32 s100, s100, s101
	s_lshl_b32 s12, s100, 10
	s_add_u32 s8, s46, s12
	s_addc_u32 s9, s47, 0
	global_load_dwordx4 v[30:33], v64, s[8:9]
	s_add_u32 s8, s48, s12
	s_addc_u32 s9, s49, 0
	global_load_dwordx4 v[34:37], v64, s[8:9]
	s_mul_i32 s12, s100, 0x1600
	s_add_u32 s8, s38, s12
	s_addc_u32 s9, s39, 0
	global_load_dwordx2 v[38:39], v65, s[8:9]
	s_add_u32 s101, s101, 8
	s_cmp_gt_u32 s101, s15
	s_cbranch_scc1 .Lhfu_exit
; __device__ __forceinline__ unsigned pk2(float lo, float hi) { f32x2_t v = {lo, hi}; bf16x2_t b = __builtin_convertvector(v, bf16x2_t); return __builtin_bit_cast(unsigned, b); }
; __device__ __forceinline__ float shx(float v, int o, int lane) { return __builtin_bit_cast(float, __builtin_amdgcn_ds_bpermute((lane ^ o) << 2, __builtin_bit_cast(int, v))); }
; __device__ __forceinline__ float sigmoidf_(float z) { return __builtin_amdgcn_rcpf(1.0f + fast_exp2(-z * LOG2E)); }
; __device__ __forceinline__ void phase_hfin(const Params& P, int l) {
;     ...
;         for (int u = 0; u < 3; ++u) {
;             const long i = i0 + u * S; const bool ok = i < total; const long rh = (ok ? i : i0) >> 4; const int h = (int)(rh & 3); const long r = rh >> 2;
;             const size_t off = (size_t)r * 256 + h * 64 + sub * 4;
;             a[u] = *(const f32x4*)(od0 + off); b2[u] = *(const f32x4*)(od1 + off);
;             gw[u] = *(const u32x2*)(proj + (size_t)r * INW + PB_G + h * 64 + sub * 4);
;         }
; #pragma unroll
;         for (int u = 0; u < 3; ++u) {
;             const long i = i0 + u * S; if (i >= total) break;
;             const long rh = i >> 4; const int h = (int)(rh & 3); const long r = rh >> 2;
;             const f32x4 o = a[u] + b2[u];
;             float ss = (o.x * o.x + o.y * o.y) + (o.z * o.z + o.w * o.w);
;             ss += shx(ss, 1, lane); ss += shx(ss, 2, lane); ss += shx(ss, 4, lane); ss += shx(ss, 8, lane);
;             const float rs = 1.0f / sqrtf(ss * (1.0f / 64.0f) + RMS_EPS);
;             const float g0 = bflo(gw[u].x), g1 = bfhi(gw[u].x), g2 = bflo(gw[u].y), g3 = bfhi(gw[u].y);
;             u32x2 w; w.x = pk2(o.x * rs * gg.x * (g0 * sigmoidf_(g0)), o.y * rs * gg.y * (g1 * sigmoidf_(g1))); w.y = pk2(o.z * rs * gg.z * (g2 * sigmoidf_(g2)), o.w * rs * gg.w * (g3 * sigmoidf_(g3)));
;             *(u32x2*)(mix + (size_t)r * DM + 256 + h * 64 + sub * 4) = w;
	s_waitcnt vmcnt(20)
	v_add_f32_e32 v72, v40, v44
	v_add_f32_e32 v73, v41, v45
	v_add_f32_e32 v74, v42, v46
	v_add_f32_e32 v75, v43, v47
	v_lshlrev_b32_e32 v84, 16, v48
	v_and_b32_e32 v85, 0xffff0000, v48
	v_lshlrev_b32_e32 v86, 16, v49
	v_and_b32_e32 v87, 0xffff0000, v49
	v_mul_f32_e32 v76, v73, v73
	v_mul_f32_e32 v77, v75, v75
	v_fmac_f32_e32 v76, v72, v72
	v_fmac_f32_e32 v77, v74, v74
	v_add_f32_e32 v78, v76, v77
	ds_bpermute_b32 v76, v67, v78
	v_mul_f32_e32 v88, 0xbfb8aa3b, v84
	v_mul_f32_e32 v89, 0xbfb8aa3b, v85
	v_mul_f32_e32 v90, 0xbfb8aa3b, v86
	v_mul_f32_e32 v91, 0xbfb8aa3b, v87
	s_waitcnt lgkmcnt(0)
	v_add_f32_e32 v78, v78, v76
	ds_bpermute_b32 v76, v68, v78
	v_exp_f32_e32 v88, v88
	v_exp_f32_e32 v89, v89
	v_exp_f32_e32 v90, v90
	v_exp_f32_e32 v91, v91
	s_waitcnt lgkmcnt(0)
	v_add_f32_e32 v78, v78, v76
	ds_bpermute_b32 v76, v69, v78
	v_add_f32_e32 v88, 1.0, v88
	v_add_f32_e32 v89, 1.0, v89
	v_add_f32_e32 v90, 1.0, v90
	v_add_f32_e32 v91, 1.0, v91
	s_waitcnt lgkmcnt(0)
	v_add_f32_e32 v78, v78, v76
	ds_bpermute_b32 v76, v70, v78
	v_rcp_f32_e32 v88, v88
	v_rcp_f32_e32 v89, v89
	v_rcp_f32_e32 v90, v90
	v_rcp_f32_e32 v91, v91
	s_waitcnt lgkmcnt(0)
	v_add_f32_e32 v78, v78, v76
	v_mul_f32_e32 v88, v88, v84
	v_mul_f32_e32 v89, v89, v85
	v_mul_f32_e32 v90, v90, v86
	v_mul_f32_e32 v91, v91, v87
	v_fmamk_f32 v78, v78, 0x3c800000, v201
	v_mul_f32_e32 v76, 0x4f800000, v78
	v_cmp_gt_f32_e32 vcc, 0xf800000, v78
	s_nop 1
	v_cndmask_b32_e32 v78, v78, v76, vcc
	v_sqrt_f32_e32 v76, v78
	s_nop 0
	v_add_u32_e32 v79, -1, v76
	v_add_u32_e32 v80, 1, v76
	v_fma_f32 v81, -v79, v76, v78
	v_fma_f32 v82, -v80, v76, v78
	v_cmp_ge_f32_e64 s[42:43], 0, v81
	s_nop 1
	v_cndmask_b32_e64 v76, v76, v79, s[42:43]
	v_cmp_lt_f32_e64 s[42:43], 0, v82
	s_nop 1
	v_cndmask_b32_e64 v76, v76, v80, s[42:43]
	v_mul_f32_e32 v79, 0x37800000, v76
	v_cndmask_b32_e32 v76, v76, v79, vcc
	v_cmp_class_f32_e32 vcc, v78, v202
	s_nop 1
	v_cndmask_b32_e32 v78, v76, v78, vcc
	v_div_scale_f32 v76, s[42:43], v78, v78, 1.0
	v_rcp_f32_e32 v79, v76
	v_div_scale_f32 v80, vcc, 1.0, v78, 1.0
	v_fma_f32 v81, -v76, v79, 1.0
	v_fmac_f32_e32 v79, v81, v79
	v_mul_f32_e32 v81, v80, v79
	v_fma_f32 v82, -v76, v81, v80
	v_fmac_f32_e32 v81, v82, v79
	v_fma_f32 v76, -v76, v81, v80
	v_div_fmas_f32 v76, v76, v79, v81
	v_div_fixup_f32 v83, v76, v78, 1.0
	v_mul_f32_e32 v92, v72, v83
	v_mul_f32_e32 v92, v60, v92
	v_mul_f32_e32 v92, v88, v92
	v_mul_f32_e32 v93, v73, v83
	v_mul_f32_e32 v93, v61, v93
	v_mul_f32_e32 v93, v89, v93
	v_mul_f32_e32 v94, v74, v83
	v_mul_f32_e32 v94, v62, v94
	v_mul_f32_e32 v94, v90, v94
	v_mul_f32_e32 v95, v75, v83
	v_mul_f32_e32 v95, v63, v95
	v_mul_f32_e32 v95, v91, v95
	v_cvt_pk_bf16_f32 v96, v92, v93
	v_cvt_pk_bf16_f32 v97, v94, v95
	s_lshl_b32 s12, s101, 11
	s_add_u32 s8, s40, s12
	s_addc_u32 s9, s41, 0
	global_store_dwordx2 v65, v[96:97], s[8:9]
	s_mul_i32 s100, 8, 6
	s_add_u32 s100, s100, s101
	s_cmp_le_u32 s100, s15
	s_cselect_b32 s100, s100, s101
	s_lshl_b32 s12, s100, 10
	s_add_u32 s8, s46, s12
	s_addc_u32 s9, s47, 0
	global_load_dwordx4 v[40:43], v64, s[8:9]
	s_add_u32 s8, s48, s12
	s_addc_u32 s9, s49, 0
	global_load_dwordx4 v[44:47], v64, s[8:9]
	s_mul_i32 s12, s100, 0x1600
	s_add_u32 s8, s38, s12
	s_addc_u32 s9, s39, 0
	global_load_dwordx2 v[48:49], v65, s[8:9]
	s_add_u32 s101, s101, 8
	s_cmp_gt_u32 s101, s15
	s_cbranch_scc1 .Lhfu_exit
	s_waitcnt vmcnt(20)
	v_add_f32_e32 v72, v50, v54
	v_add_f32_e32 v73, v51, v55
	v_add_f32_e32 v74, v52, v56
	v_add_f32_e32 v75, v53, v57
	v_lshlrev_b32_e32 v84, 16, v58
	v_and_b32_e32 v85, 0xffff0000, v58
	v_lshlrev_b32_e32 v86, 16, v59
	v_and_b32_e32 v87, 0xffff0000, v59
	v_mul_f32_e32 v76, v73, v73
	v_mul_f32_e32 v77, v75, v75
	v_fmac_f32_e32 v76, v72, v72
	v_fmac_f32_e32 v77, v74, v74
	v_add_f32_e32 v78, v76, v77
	ds_bpermute_b32 v76, v67, v78
	v_mul_f32_e32 v88, 0xbfb8aa3b, v84
	v_mul_f32_e32 v89, 0xbfb8aa3b, v85
	v_mul_f32_e32 v90, 0xbfb8aa3b, v86
	v_mul_f32_e32 v91, 0xbfb8aa3b, v87
	s_waitcnt lgkmcnt(0)
	v_add_f32_e32 v78, v78, v76
	ds_bpermute_b32 v76, v68, v78
	v_exp_f32_e32 v88, v88
	v_exp_f32_e32 v89, v89
	v_exp_f32_e32 v90, v90
	v_exp_f32_e32 v91, v91
	s_waitcnt lgkmcnt(0)
	v_add_f32_e32 v78, v78, v76
	ds_bpermute_b32 v76, v69, v78
	v_add_f32_e32 v88, 1.0, v88
	v_add_f32_e32 v89, 1.0, v89
	v_add_f32_e32 v90, 1.0, v90
	v_add_f32_e32 v91, 1.0, v91
	s_waitcnt lgkmcnt(0)
	v_add_f32_e32 v78, v78, v76
	ds_bpermute_b32 v76, v70, v78
	v_rcp_f32_e32 v88, v88
	v_rcp_f32_e32 v89, v89
	v_rcp_f32_e32 v90, v90
	v_rcp_f32_e32 v91, v91
	s_waitcnt lgkmcnt(0)
	v_add_f32_e32 v78, v78, v76
	v_mul_f32_e32 v88, v88, v84
	v_mul_f32_e32 v89, v89, v85
	v_mul_f32_e32 v90, v90, v86
	v_mul_f32_e32 v91, v91, v87
	v_fmamk_f32 v78, v78, 0x3c800000, v201
	v_mul_f32_e32 v76, 0x4f800000, v78
	v_cmp_gt_f32_e32 vcc, 0xf800000, v78
	s_nop 1
	v_cndmask_b32_e32 v78, v78, v76, vcc
	v_sqrt_f32_e32 v76, v78
	s_nop 0
	v_add_u32_e32 v79, -1, v76
	v_add_u32_e32 v80, 1, v76
	v_fma_f32 v81, -v79, v76, v78
	v_fma_f32 v82, -v80, v76, v78
	v_cmp_ge_f32_e64 s[42:43], 0, v81
	s_nop 1
	v_cndmask_b32_e64 v76, v76, v79, s[42:43]
	v_cmp_lt_f32_e64 s[42:43], 0, v82
	s_nop 1
	v_cndmask_b32_e64 v76, v76, v80, s[42:43]
	v_mul_f32_e32 v79, 0x37800000, v76
	v_cndmask_b32_e32 v76, v76, v79, vcc
	v_cmp_class_f32_e32 vcc, v78, v202
	s_nop 1
	v_cndmask_b32_e32 v78, v76, v78, vcc
	v_div_scale_f32 v76, s[42:43], v78, v78, 1.0
	v_rcp_f32_e32 v79, v76
	v_div_scale_f32 v80, vcc, 1.0, v78, 1.0
	v_fma_f32 v81, -v76, v79, 1.0
	v_fmac_f32_e32 v79, v81, v79
	v_mul_f32_e32 v81, v80, v79
	v_fma_f32 v82, -v76, v81, v80
	v_fmac_f32_e32 v81, v82, v79
	v_fma_f32 v76, -v76, v81, v80
	v_div_fmas_f32 v76, v76, v79, v81
	v_div_fixup_f32 v83, v76, v78, 1.0
	v_mul_f32_e32 v92, v72, v83
	v_mul_f32_e32 v92, v60, v92
	v_mul_f32_e32 v92, v88, v92
	v_mul_f32_e32 v93, v73, v83
	v_mul_f32_e32 v93, v61, v93
	v_mul_f32_e32 v93, v89, v93
	v_mul_f32_e32 v94, v74, v83
	v_mul_f32_e32 v94, v62, v94
	v_mul_f32_e32 v94, v90, v94
	v_mul_f32_e32 v95, v75, v83
	v_mul_f32_e32 v95, v63, v95
	v_mul_f32_e32 v95, v91, v95
	v_cvt_pk_bf16_f32 v96, v92, v93
	v_cvt_pk_bf16_f32 v97, v94, v95
	s_lshl_b32 s12, s101, 11
	s_add_u32 s8, s40, s12
	s_addc_u32 s9, s41, 0
	global_store_dwordx2 v65, v[96:97], s[8:9]
	s_mul_i32 s100, 8, 6
	s_add_u32 s100, s100, s101
	s_cmp_le_u32 s100, s15
	s_cselect_b32 s100, s100, s101
	s_lshl_b32 s12, s100, 10
	s_add_u32 s8, s46, s12
	s_addc_u32 s9, s47, 0
	global_load_dwordx4 v[50:53], v64, s[8:9]
	s_add_u32 s8, s48, s12
	s_addc_u32 s9, s49, 0
	global_load_dwordx4 v[54:57], v64, s[8:9]
	s_mul_i32 s12, s100, 0x1600
	s_add_u32 s8, s38, s12
	s_addc_u32 s9, s39, 0
	global_load_dwordx2 v[58:59], v65, s[8:9]
	s_add_u32 s101, s101, 8
	s_cmp_gt_u32 s101, s15
	s_cbranch_scc1 .Lhfu_exit
	s_branch .Lhfu_loop
.Lhfu_exit:
	s_waitcnt vmcnt(0)
.LBB0_348:
	s_barrier
	s_waitcnt vmcnt(0)
	s_barrier

; template <int DK, bool IS_A>
; __device__ __forceinline__ void attn_unit(const Params& P, int l, LAS unsigned char* lds, int b, int grp, int qtok0, int nkeys) {
;     const int tid = opaque_tid(), lane = tid & 63, wave = tid >> 6, s = wave >> 2, wq = wave & 3, r32 = lane & 31, hi = lane >> 5;
;     const bf16_t* proj = (const bf16_t*)(P.ws + WS_PROJ);
;     bf16_t* mix = (bf16_t*)(P.ws + WS_H);
;     const int qcol = IS_A ? PA_Q + grp * 64 + s * 32 : PC_Q + (2 * grp + s) * 64;
;     const int kcol = IS_A ? PA_K + grp * 64 : PC_K + grp * 64;
;     const int koff = IS_A ? s * 32 : 0;
;     const bf16_t* VT = IS_A ? (const bf16_t*)(P.ws + WS_VTA) + ((size_t)(b * 4 + grp) * 64) * TT : (const bf16_t*)(P.ws + WS_VTC) + ((size_t)(b * 2 + grp) * 64) * TT;
;     const size_t qrow = (size_t)b * TT + qtok0 + wq * 64 + r32;
;     ...
;     for (;;) {
;         if (opaque_tid() == 0) *slot = (int)atomicAdd(ctr, 1u);
;         __syncthreads();
;         int it = *slot;
;         __syncthreads();
;         if (it >= total) break;
;         if (it < N_F) {
;             pg8::Gemm g{(const pg8::bf16_t*)(P.ws + WS_FMAT), (const pg8::bf16_t*)(P.ws + WS_ZT), SEQ, NBATCH * 256, 2048}; OneUnit S{it & 7, it >> 3};
;             pg8::EpiBf16<0> E{(pg8::bf16_t*)(P.ws + WS_H) + (size_t)CTX * DM + 768, DM, nullptr, 256, (size_t)TT * DM, 1.0f};
;             pg8::gemm_phase<pg8::EpiBf16<0>, OneUnit, false, true>(lds, g, S, E); __syncthreads(); continue; } it -= N_F;
;         if (it < N_H) { hgrn_mfma_unit(P, l, lds, it >> 1, it & 1); continue; } it -= N_H;
;         if (it < N_C) { attn_unit<64, false>(P, l, lds, it >> 4, (it >> 3) & 1, CTX + (it & 7) * 256, TT); continue; } it -= N_C;
;         if (it < N_A) { attn_unit<32, true>(P, l, lds, it >> 5, (it >> 3) & 3, CTX + (it & 7) * 256, TT); continue; } it -= N_A;
;         if (it < N_FC) {
;             pg8::Gemm g{(const pg8::bf16_t*)(P.ws + WS_FC), (const pg8::bf16_t*)(P.ws + WS_ZCT), CTX, NBATCH * 256, 512}; OneUnit S{0, it};
;             pg8::EpiBf16<0> E{(pg8::bf16_t*)(P.ws + WS_H) + 768, DM, nullptr, 256, (size_t)TT * DM, 1.0f};
;             pg8::gemm_phase<pg8::EpiBf16<0>, OneUnit, false, true>(lds, g, S, E); __syncthreads(); continue; } it -= N_FC;
;         if (it < N_AC) { attn_unit<32, true>(P, l, lds, it >> 2, it & 3, 0, CTX); continue; } it -= N_AC;
;         attn_unit<64, false>(P, l, lds, it >> 1, it & 1, 0, CTX);
.LBB0_355:
	s_or_b64 exec, exec, s[10:11]
	v_readlane_b32 s7, v254, 26
	s_waitcnt lgkmcnt(0)
	s_barrier
	v_mov_b32_e32 v0, s7
	ds_read_b32 v0, v0
	s_mov_b64 s[10:11], -1
	s_waitcnt lgkmcnt(0)
	s_barrier
	v_cmp_le_i32_e32 vcc, s29, v0
	v_readfirstlane_b32 s37, v0
	s_cbranch_vccnz .LBB0_350
	s_cmp_lg_u32 s60, 0x100
	s_cbranch_scc1 .Lhfu_no
	s_sub_u32 s8, s29, 0x100
	s_cmp_ge_u32 s37, s8
	s_cbranch_scc1 .Lhfu_unit
.Lhfu_no:
	s_cmpk_gt_i32 s37, 0x7f
	s_cbranch_scc0 .LBB0_720
	s_cmpk_gt_u32 s37, 0x9f
	s_cbranch_scc0 .LBB0_461
	s_cmpk_gt_u32 s37, 0x19f
	s_cbranch_scc0 .LBB0_440
	s_cmpk_gt_u32 s37, 0x39f
	s_cbranch_scc0 .LBB0_415
	s_cmpk_gt_u32 s37, 0x3af
	s_cbranch_scc0 .LBB0_406
	s_cmpk_gt_u32 s37, 0x3ef
	s_cbranch_scc0 .LBB0_381
	s_add_i32 s8, s37, 0xfffffc10
	s_lshr_b32 s9, s8, 1
	s_and_b32 s10, s37, 1
	v_mov_b32_e32 v12, v200
	s_lshl_b32 s8, s10, 7
	s_lshl_b32 s10, s10, 6
	s_lshl_b32 s11, s9, 7
	s_or_b32 s10, s11, s10
	v_ashrrev_i32_e32 v2, 3, v12
	s_mul_i32 s64, s10, 0x900
	s_mul_i32 s10, s9, 0x900
	s_mov_b32 s11, s65
	v_ashrrev_i32_e32 v3, 31, v2
	v_mov_b64_e32 v[0:1], s[56:57]
	s_lshl_b64 s[12:13], s[64:65], 1
	v_lshl_add_u64 v[4:5], v[2:3], 0, s[10:11]
	s_add_u32 s12, s20, s12
	v_readlane_b32 s7, v255, 5
	v_mad_u64_u32 v[6:7], s[18:19], v4, s23, v[0:1]
	s_addc_u32 s13, s7, s13
	v_mad_i32_i24 v7, v5, s23, v7
	s_mov_b32 s9, s65
	v_lshlrev_b32_e32 v3, 4, v12
	v_lshl_add_u64 v[4:5], v[6:7], 0, s[8:9]
	v_and_b32_e32 v190, 0x70, v3
	v_mov_b32_e32 v191, v129
	v_mov_b64_e32 v[6:7], s[12:13]
	v_lshl_add_u64 v[4:5], v[4:5], 0, v[190:191]
	v_mad_i64_i32 v[6:7], s[12:13], v2, s27, v[6:7]
	s_movk_i32 s7, 0x1000
	v_lshl_add_u64 v[192:193], v[6:7], 0, v[190:191]
	v_add_co_u32_e32 v6, vcc, s7, v4
	s_mov_b32 s9, 0x59000
	s_nop 0
	v_addc_co_u32_e32 v7, vcc, 0, v5, vcc
	v_add_co_u32_e32 v8, vcc, s9, v4
	v_and_b32_e32 v3, 0xc0, v12
	s_nop 0
	v_addc_co_u32_e32 v9, vcc, 0, v5, vcc
	global_load_dwordx4 v[130:133], v[6:7], off offset:512
	global_load_dwordx4 v[134:137], v[8:9], off offset:512
	global_load_dwordx4 v[138:141], v[192:193], off
	global_load_dwordx4 v[142:145], v[192:193], off offset:128
	v_ashrrev_i32_e32 v6, 2, v12
	v_and_b32_e32 v13, 31, v12
	v_and_b32_e32 v6, 0xffffffc0, v6
	v_add_u32_e32 v188, s8, v6
	v_or3_b32 v128, v3, s10, v13
	v_bfe_u32 v14, v12, 5, 1
	v_mad_u64_u32 v[0:1], s[8:9], v128, s23, v[0:1]
	v_ashrrev_i32_e32 v189, 31, v188
	v_lshl_add_u64 v[0:1], v[188:189], 1, v[0:1]
	v_lshlrev_b32_e32 v194, 4, v14
	v_mov_b32_e32 v195, v129
	v_lshl_add_u64 v[0:1], v[0:1], 0, v[194:195]
	s_mov_b64 s[8:9], 0x1000
	v_add_co_u32_e32 v10, vcc, s7, v0
	v_lshl_add_u64 v[6:7], v[0:1], 0, s[8:9]
	s_mov_b64 s[8:9], 0x2d000
	v_addc_co_u32_e32 v11, vcc, 0, v1, vcc
	s_mov_b32 s7, 0x2d000
	v_lshl_add_u64 v[8:9], v[0:1], 0, s[8:9]
	v_add_co_u32_e32 v0, vcc, s7, v0
	s_movk_i32 s7, 0x90
	s_nop 0
	v_addc_co_u32_e32 v1, vcc, 0, v1, vcc
	global_load_dwordx4 v[146:149], v[10:11], off
	global_load_dwordx4 v[150:153], v[0:1], off
	global_load_dwordx4 v[154:157], v[6:7], off offset:32
	global_load_dwordx4 v[158:161], v[6:7], off offset:64
	global_load_dwordx4 v[162:165], v[8:9], off offset:32
	global_load_dwordx4 v[166:169], v[6:7], off offset:96
	global_load_dwordx4 v[170:173], v[8:9], off offset:64
	global_load_dwordx4 v[174:177], v[8:9], off offset:96
	v_mul_lo_u32 v0, v2, s7
	s_movk_i32 s7, 0x78
	v_and_b32_e32 v1, 63, v12
	v_mul_lo_u32 v3, v2, s7
	v_add_u32_e32 v0, 0, v0
	v_add_u32_e32 v6, v0, v190
	v_add_u32_e32 v0, v0, v3
	s_mov_b64 s[10:11], 0x1200
	v_lshlrev_b32_e32 v1, 2, v1
	s_movk_i32 s7, 0xff88
	v_add_u32_e32 v7, v0, v190
	v_lshl_add_u64 v[196:197], v[4:5], 0, s[10:11]
	v_mad_u64_u32 v[198:199], s[10:11], v2, s7, v[0:1]
	v_lshlrev_b32_e32 v186, 3, v14
	v_add_u32_e32 v8, 0x4800, v7
	v_add_u32_e32 v7, 0x4880, v7
	v_add_u32_e32 v16, v198, v3
	v_mov_b32_e32 v14, v129
	v_mov_b32_e32 v15, v129
	s_waitcnt vmcnt(17)
	v_mul_u32_u24_e32 v178, 0x90, v13
	s_waitcnt vmcnt(11)
	ds_write_b128 v6, v[130:133]
	s_waitcnt vmcnt(10)
	ds_write_b128 v6, v[134:137] offset:9216
	s_waitcnt vmcnt(9)
	ds_write2_b64 v8, v[138:139], v[140:141] offset1:1
	s_waitcnt vmcnt(8)
	ds_write2_b64 v7, v[142:143], v[144:145] offset1:1
	v_mul_u32_u24_e32 v180, 0x108, v13
	v_xor_b32_e32 v179, 0x80, v1
	v_mov_b32_e32 v0, v129
	v_mov_b32_e32 v1, v129
	v_mov_b32_e32 v2, v129
	v_mov_b32_e32 v3, v129
	v_mov_b32_e32 v4, v129
	v_mov_b32_e32 v5, v129
	v_mov_b32_e32 v6, v129
	v_mov_b32_e32 v7, v129
	v_mov_b32_e32 v8, v129
	v_mov_b32_e32 v9, v129
	v_mov_b32_e32 v10, v129
	v_mov_b32_e32 v11, v129
	v_mov_b32_e32 v12, v129
	v_mov_b32_e32 v13, v129
	v_add_u32_e32 v181, v16, v190
	v_mov_b64_e32 v[30:31], v[14:15]
	v_mov_b64_e32 v[46:47], v[14:15]
	v_mov_b64_e32 v[62:63], v[14:15]
	s_mov_b32 s9, 0
	s_mov_b64 s[10:11], -1
	v_mov_b32_e32 v191, 0
	v_mov_b32_e32 v185, 0xf149f2ca
	v_mov_b32_e32 v187, 0xf149f2ca
	v_mov_b32_e32 v182, 0
	v_mov_b64_e32 v[28:29], v[12:13]
	v_mov_b64_e32 v[26:27], v[10:11]
	v_mov_b64_e32 v[24:25], v[8:9]
	v_mov_b64_e32 v[22:23], v[6:7]
	v_mov_b64_e32 v[20:21], v[4:5]
	v_mov_b64_e32 v[18:19], v[2:3]
	v_mov_b64_e32 v[16:17], v[0:1]
	v_mov_b64_e32 v[44:45], v[12:13]
	v_mov_b64_e32 v[42:43], v[10:11]
	v_mov_b64_e32 v[40:41], v[8:9]
	v_mov_b64_e32 v[38:39], v[6:7]
	v_mov_b64_e32 v[36:37], v[4:5]
	v_mov_b64_e32 v[34:35], v[2:3]
	v_mov_b64_e32 v[32:33], v[0:1]
	v_mov_b64_e32 v[60:61], v[12:13]
	v_mov_b64_e32 v[58:59], v[10:11]
	v_mov_b64_e32 v[56:57], v[8:9]
	v_mov_b64_e32 v[54:55], v[6:7]
	v_mov_b64_e32 v[52:53], v[4:5]
	v_mov_b64_e32 v[50:51], v[2:3]
	v_mov_b64_e32 v[48:49], v[0:1]
	s_waitcnt lgkmcnt(0)
	s_waitcnt vmcnt(0)
	s_barrier
	s_branch .LBB0_364

; __device__ __forceinline__ void hgrn_mfma_unit(const Params& P, int l, LAS unsigned char* lds, int b, int half) {
;     ...
;     }
;     __syncthreads();
.LBB0_718:
	s_or_b64 exec, exec, s[10:11]
	v_mov_b32_e32 v242, v203
	v_mov_b32_e32 v203, v201
	v_mov_b32_e32 v201, v202
	v_mov_b32_e32 v202, 0x260
	s_waitcnt vmcnt(0)
	s_barrier
	v_readfirstlane_b32 s7, v200
	v_readlane_b32 s8, v254, 55
	v_readlane_b32 s9, v254, 56
	s_nop 3
	s_lshr_b32 s7, s7, 6
	s_cmp_lg_u32 s7, 0
	s_cbranch_scc1 .Lhgsig_skip
	s_load_dwordx2 s[8:9], s[8:9], 0xa0
	buffer_wbl2 sc1
	v_mov_b32_e32 v0, 1
	s_waitcnt vmcnt(0) lgkmcnt(0)
	s_mov_b64 s[12:13], exec
	s_mov_b64 exec, 1
	global_atomic_add v129, v0, s[8:9] offset:576
	s_mov_b64 exec, s[12:13]

; __device__ __forceinline__ int opaque_tid() { int t = threadIdx.x; asm volatile("" : "+v"(t)); return t; }
; __device__ __forceinline__ unsigned pk2(float lo, float hi) { f32x2_t v = {lo, hi}; bf16x2_t b = __builtin_convertvector(v, bf16x2_t); return __builtin_bit_cast(unsigned, b); }
; __device__ __forceinline__ void phase_hfin(const Params& P, int l) {
;     const float* od0 = (const float*)(P.ws + WS_ODIR); const float* od1 = od0 + (size_t)ROWS * 256;
;     const bf16_t* proj = (const bf16_t*)(P.ws + WS_PROJ); bf16_t* mix = (bf16_t*)(P.ws + WS_H);
;     const float* gn = P.hgrn_norm + (size_t)l * 64;
;     const long total = (long)ROWS * 4 * 16;
;     const int tid = opaque_tid(), lane = tid & 63;
;     const long S = (long)gridDim.x * 512;
;     const int sub = tid & 15; const f32x4 gg = *(const f32x4*)(gn + sub * 4);
;     for (long i0 = (long)blockIdx.x * 512 + tid; i0 < total; i0 += 3 * S) {
;         f32x4 a[3], b2[3]; u32x2 gw[3];
; #pragma unroll
;         for (int u = 0; u < 3; ++u) {
;             const long i = i0 + u * S; const bool ok = i < total; const long rh = (ok ? i : i0) >> 4; const int h = (int)(rh & 3); const long r = rh >> 2;
;             const size_t off = (size_t)r * 256 + h * 64 + sub * 4;
;             a[u] = *(const f32x4*)(od0 + off); b2[u] = *(const f32x4*)(od1 + off);
;             gw[u] = *(const u32x2*)(proj + (size_t)r * INW + PB_G + h * 64 + sub * 4);
;         }
; #pragma unroll
;         for (int u = 0; u < 3; ++u) {
;             const long i = i0 + u * S; if (i >= total) break;
;             const long rh = i >> 4; const int h = (int)(rh & 3); const long r = rh >> 2;
;             const f32x4 o = a[u] + b2[u];
;             float ss = (o.x * o.x + o.y * o.y) + (o.z * o.z + o.w * o.w);
;             ss += shx(ss, 1, lane); ss += shx(ss, 2, lane); ss += shx(ss, 4, lane); ss += shx(ss, 8, lane);
;             const float rs = 1.0f / sqrtf(ss * (1.0f / 64.0f) + RMS_EPS);
;             const float g0 = bflo(gw[u].x), g1 = bfhi(gw[u].x), g2 = bflo(gw[u].y), g3 = bfhi(gw[u].y);
;             u32x2 w; w.x = pk2(o.x * rs * gg.x * (g0 * sigmoidf_(g0)), o.y * rs * gg.y * (g1 * sigmoidf_(g1))); w.y = pk2(o.z * rs * gg.z * (g2 * sigmoidf_(g2)), o.w * rs * gg.w * (g3 * sigmoidf_(g3)));
;             *(u32x2*)(mix + (size_t)r * DM + 256 + h * 64 + sub * 4) = w;
.LBB0_779:
	s_or_b64 exec, exec, s[0:1]
	s_mov_b64 s[24:25], s[28:29]
	v_mov_b32_e32 v6, v200
	v_readlane_b32 s0, v253, 50
	s_waitcnt lgkmcnt(0)
	s_barrier
	v_readlane_b32 s1, v253, 51
	v_ashrrev_i32_e32 v7, 31, v6
	s_nop 0
	v_lshl_add_u64 v[4:5], s[0:1], 0, v[6:7]
	s_mov_b64 s[0:1], 0x240000
	v_cmp_gt_i64_e32 vcc, s[0:1], v[4:5]
	s_and_saveexec_b64 s[0:1], vcc
	s_xor_b64 s[0:1], exec, s[0:1]
	s_cbranch_execz .LBB0_786
	s_mov_b64 s[44:45], 0
	s_cmp_eq_u32 s60, 0x100
	s_cbranch_scc1 .LBB0_785
	s_load_dwordx2 s[10:11], s[24:25], 0xa0
	s_load_dwordx2 s[8:9], s[24:25], 0x58
	v_readlane_b32 s12, v255, 14
	v_readlane_b32 s13, v255, 15
	v_readlane_b32 s101, v253, 62
	v_readfirstlane_b32 s100, v200
	v_and_b32_e32 v64, 63, v200
	v_and_b32_e32 v66, 15, v200
	v_lshlrev_b32_e32 v66, 4, v66
	v_lshlrev_b32_e32 v65, 3, v64
	v_lshlrev_b32_e32 v76, 2, v64
	v_xor_b32_e32 v67, 4, v76
	v_xor_b32_e32 v68, 8, v76
	v_xor_b32_e32 v69, 16, v76
	v_xor_b32_e32 v70, 32, v76
	v_lshlrev_b32_e32 v64, 4, v64
	s_lshr_b32 s100, s100, 6
	s_add_u32 s101, s101, s100
	s_waitcnt lgkmcnt(0)
	s_add_u32 s8, s8, s12
	s_addc_u32 s9, s9, s13
	global_load_dwordx4 v[60:63], v66, s[8:9]
	s_add_u32 s24, s10, 0x1a200000
	s_addc_u32 s25, s11, 0
	s_add_u32 s36, s10, 0x1c600000
	s_addc_u32 s37, s11, 0
	s_add_u32 s38, s10, 0x9d00e00
	s_addc_u32 s39, s11, 0
	s_add_u32 s40, s10, 0x5500200
	s_addc_u32 s41, s11, 0
	s_lshl_b32 s12, s101, 10
	s_add_u32 s8, s24, s12
	s_addc_u32 s9, s25, 0
	global_load_dwordx4 v[0:3], v64, s[8:9]
	s_add_u32 s8, s36, s12
	s_addc_u32 s9, s37, 0
	global_load_dwordx4 v[4:7], v64, s[8:9]
	s_mul_i32 s12, s101, 0x1600
	s_add_u32 s8, s38, s12
	s_addc_u32 s9, s39, 0
	global_load_dwordx2 v[8:9], v65, s[8:9]
	s_add_u32 s100, s101, s68
	s_cmp_le_u32 s100, s71
	s_cselect_b32 s100, s100, s101
	s_lshl_b32 s12, s100, 10
	s_add_u32 s8, s24, s12
	s_addc_u32 s9, s25, 0
	global_load_dwordx4 v[10:13], v64, s[8:9]
	s_add_u32 s8, s36, s12
	s_addc_u32 s9, s37, 0
	global_load_dwordx4 v[14:17], v64, s[8:9]
	s_mul_i32 s12, s100, 0x1600
	s_add_u32 s8, s38, s12
	s_addc_u32 s9, s39, 0
	global_load_dwordx2 v[18:19], v65, s[8:9]
	s_mul_i32 s100, s68, 2
	s_add_u32 s100, s100, s101
	s_cmp_le_u32 s100, s71
	s_cselect_b32 s100, s100, s101
	s_lshl_b32 s12, s100, 10
	s_add_u32 s8, s24, s12
	s_addc_u32 s9, s25, 0
	global_load_dwordx4 v[20:23], v64, s[8:9]
	s_add_u32 s8, s36, s12
	s_addc_u32 s9, s37, 0
	global_load_dwordx4 v[24:27], v64, s[8:9]
	s_mul_i32 s12, s100, 0x1600
	s_add_u32 s8, s38, s12
	s_addc_u32 s9, s39, 0
	global_load_dwordx2 v[28:29], v65, s[8:9]
	s_mul_i32 s100, s68, 3
	s_add_u32 s100, s100, s101
	s_cmp_le_u32 s100, s71
	s_cselect_b32 s100, s100, s101
	s_lshl_b32 s12, s100, 10
	s_add_u32 s8, s24, s12
	s_addc_u32 s9, s25, 0
	global_load_dwordx4 v[30:33], v64, s[8:9]
	s_add_u32 s8, s36, s12
	s_addc_u32 s9, s37, 0
	global_load_dwordx4 v[34:37], v64, s[8:9]
	s_mul_i32 s12, s100, 0x1600
	s_add_u32 s8, s38, s12
	s_addc_u32 s9, s39, 0
	global_load_dwordx2 v[38:39], v65, s[8:9]
	s_mul_i32 s100, s68, 4
	s_add_u32 s100, s100, s101
	s_cmp_le_u32 s100, s71
	s_cselect_b32 s100, s100, s101
	s_lshl_b32 s12, s100, 10
	s_add_u32 s8, s24, s12
	s_addc_u32 s9, s25, 0
	global_load_dwordx4 v[40:43], v64, s[8:9]
	s_add_u32 s8, s36, s12
	s_addc_u32 s9, s37, 0
	global_load_dwordx4 v[44:47], v64, s[8:9]
	s_mul_i32 s12, s100, 0x1600
	s_add_u32 s8, s38, s12
	s_addc_u32 s9, s39, 0
	global_load_dwordx2 v[48:49], v65, s[8:9]
	s_mul_i32 s100, s68, 5
	s_add_u32 s100, s100, s101
	s_cmp_le_u32 s100, s71
	s_cselect_b32 s100, s100, s101
	s_lshl_b32 s12, s100, 10
	s_add_u32 s8, s24, s12
	s_addc_u32 s9, s25, 0
	global_load_dwordx4 v[50:53], v64, s[8:9]
	s_add_u32 s8, s36, s12
	s_addc_u32 s9, s37, 0
	global_load_dwordx4 v[54:57], v64, s[8:9]
	s_mul_i32 s12, s100, 0x1600
	s_add_u32 s8, s38, s12
	s_addc_u32 s9, s39, 0
	global_load_dwordx2 v[58:59], v65, s[8:9]
	s_waitcnt vmcnt(15)
	v_add_f32_e32 v72, v0, v4
	v_add_f32_e32 v73, v1, v5
	v_add_f32_e32 v74, v2, v6
	v_add_f32_e32 v75, v3, v7
	v_lshlrev_b32_e32 v84, 16, v8
	v_and_b32_e32 v85, 0xffff0000, v8
	v_lshlrev_b32_e32 v86, 16, v9
	v_and_b32_e32 v87, 0xffff0000, v9
	v_mul_f32_e32 v76, v73, v73
	v_mul_f32_e32 v77, v75, v75
	v_fmac_f32_e32 v76, v72, v72
	v_fmac_f32_e32 v77, v74, v74
	v_add_f32_e32 v78, v76, v77
	ds_bpermute_b32 v76, v67, v78
	v_mul_f32_e32 v88, 0xbfb8aa3b, v84
	v_mul_f32_e32 v89, 0xbfb8aa3b, v85
	v_mul_f32_e32 v90, 0xbfb8aa3b, v86
	v_mul_f32_e32 v91, 0xbfb8aa3b, v87
	s_waitcnt lgkmcnt(0)
	v_add_f32_e32 v78, v78, v76
	ds_bpermute_b32 v76, v68, v78
	v_exp_f32_e32 v88, v88
	v_exp_f32_e32 v89, v89
	v_exp_f32_e32 v90, v90
	v_exp_f32_e32 v91, v91
	s_waitcnt lgkmcnt(0)
	v_add_f32_e32 v78, v78, v76
	ds_bpermute_b32 v76, v69, v78
	v_add_f32_e32 v88, 1.0, v88
	v_add_f32_e32 v89, 1.0, v89
	v_add_f32_e32 v90, 1.0, v90
	v_add_f32_e32 v91, 1.0, v91
	s_waitcnt lgkmcnt(0)
	v_add_f32_e32 v78, v78, v76
	ds_bpermute_b32 v76, v70, v78
	v_rcp_f32_e32 v88, v88
	v_rcp_f32_e32 v89, v89
	v_rcp_f32_e32 v90, v90
	v_rcp_f32_e32 v91, v91
	s_waitcnt lgkmcnt(0)
; __device__ __forceinline__ unsigned pk2(float lo, float hi) { f32x2_t v = {lo, hi}; bf16x2_t b = __builtin_convertvector(v, bf16x2_t); return __builtin_bit_cast(unsigned, b); }
; __device__ __forceinline__ float shx(float v, int o, int lane) { return __builtin_bit_cast(float, __builtin_amdgcn_ds_bpermute((lane ^ o) << 2, __builtin_bit_cast(int, v))); }
; __device__ __forceinline__ float sigmoidf_(float z) { return __builtin_amdgcn_rcpf(1.0f + fast_exp2(-z * LOG2E)); }
; __device__ __forceinline__ void phase_hfin(const Params& P, int l) {
;     ...
;         for (int u = 0; u < 3; ++u) {
;             const long i = i0 + u * S; const bool ok = i < total; const long rh = (ok ? i : i0) >> 4; const int h = (int)(rh & 3); const long r = rh >> 2;
;             const size_t off = (size_t)r * 256 + h * 64 + sub * 4;
;             a[u] = *(const f32x4*)(od0 + off); b2[u] = *(const f32x4*)(od1 + off);
;             gw[u] = *(const u32x2*)(proj + (size_t)r * INW + PB_G + h * 64 + sub * 4);
;         }
; #pragma unroll
;         for (int u = 0; u < 3; ++u) {
;             const long i = i0 + u * S; if (i >= total) break;
;             const long rh = i >> 4; const int h = (int)(rh & 3); const long r = rh >> 2;
;             const f32x4 o = a[u] + b2[u];
;             float ss = (o.x * o.x + o.y * o.y) + (o.z * o.z + o.w * o.w);
;             ss += shx(ss, 1, lane); ss += shx(ss, 2, lane); ss += shx(ss, 4, lane); ss += shx(ss, 8, lane);
;             const float rs = 1.0f / sqrtf(ss * (1.0f / 64.0f) + RMS_EPS);
;             const float g0 = bflo(gw[u].x), g1 = bfhi(gw[u].x), g2 = bflo(gw[u].y), g3 = bfhi(gw[u].y);
;             u32x2 w; w.x = pk2(o.x * rs * gg.x * (g0 * sigmoidf_(g0)), o.y * rs * gg.y * (g1 * sigmoidf_(g1))); w.y = pk2(o.z * rs * gg.z * (g2 * sigmoidf_(g2)), o.w * rs * gg.w * (g3 * sigmoidf_(g3)));
;             *(u32x2*)(mix + (size_t)r * DM + 256 + h * 64 + sub * 4) = w;
	v_add_f32_e32 v78, v78, v76
	v_mul_f32_e32 v88, v88, v84
	v_mul_f32_e32 v89, v89, v85
	v_mul_f32_e32 v90, v90, v86
	v_mul_f32_e32 v91, v91, v87
	v_fmamk_f32 v78, v78, 0x3c800000, v201
	v_mul_f32_e32 v76, 0x4f800000, v78
	v_cmp_gt_f32_e32 vcc, 0xf800000, v78
	s_nop 1
	v_cndmask_b32_e32 v78, v78, v76, vcc
	v_sqrt_f32_e32 v76, v78
	s_nop 0
	v_add_u32_e32 v79, -1, v76
	v_add_u32_e32 v80, 1, v76
	v_fma_f32 v81, -v79, v76, v78
	v_fma_f32 v82, -v80, v76, v78
	v_cmp_ge_f32_e64 s[42:43], 0, v81
	s_nop 1
	v_cndmask_b32_e64 v76, v76, v79, s[42:43]
	v_cmp_lt_f32_e64 s[42:43], 0, v82
	s_nop 1
	v_cndmask_b32_e64 v76, v76, v80, s[42:43]
	v_mul_f32_e32 v79, 0x37800000, v76
	v_cndmask_b32_e32 v76, v76, v79, vcc
	v_cmp_class_f32_e32 vcc, v78, v202
	s_nop 1
	v_cndmask_b32_e32 v78, v76, v78, vcc
	v_div_scale_f32 v76, s[42:43], v78, v78, 1.0
	v_rcp_f32_e32 v79, v76
	v_div_scale_f32 v80, vcc, 1.0, v78, 1.0
	v_fma_f32 v81, -v76, v79, 1.0
	v_fmac_f32_e32 v79, v81, v79
	v_mul_f32_e32 v81, v80, v79
	v_fma_f32 v82, -v76, v81, v80
	v_fmac_f32_e32 v81, v82, v79
	v_fma_f32 v76, -v76, v81, v80
	v_div_fmas_f32 v76, v76, v79, v81
	v_div_fixup_f32 v83, v76, v78, 1.0
	v_mul_f32_e32 v92, v72, v83
	v_mul_f32_e32 v92, v60, v92
	v_mul_f32_e32 v92, v88, v92
	v_mul_f32_e32 v93, v73, v83
	v_mul_f32_e32 v93, v61, v93
	v_mul_f32_e32 v93, v89, v93
	v_mul_f32_e32 v94, v74, v83
	v_mul_f32_e32 v94, v62, v94
	v_mul_f32_e32 v94, v90, v94
	v_mul_f32_e32 v95, v75, v83
	v_mul_f32_e32 v95, v63, v95
	v_mul_f32_e32 v95, v91, v95
	v_cvt_pk_bf16_f32 v96, v92, v93
	v_cvt_pk_bf16_f32 v97, v94, v95
	s_lshl_b32 s12, s101, 11
	s_add_u32 s8, s40, s12
	s_addc_u32 s9, s41, 0
	global_store_dwordx2 v65, v[96:97], s[8:9]
	s_mul_i32 s100, s68, 6
	s_add_u32 s100, s100, s101
	s_cmp_le_u32 s100, s71
	s_cselect_b32 s100, s100, s101
	s_lshl_b32 s12, s100, 10
	s_add_u32 s8, s24, s12
	s_addc_u32 s9, s25, 0
	global_load_dwordx4 v[0:3], v64, s[8:9]
	s_add_u32 s8, s36, s12
	s_addc_u32 s9, s37, 0
	global_load_dwordx4 v[4:7], v64, s[8:9]
	s_mul_i32 s12, s100, 0x1600
	s_add_u32 s8, s38, s12
	s_addc_u32 s9, s39, 0
	global_load_dwordx2 v[8:9], v65, s[8:9]
	s_add_u32 s101, s101, s68
	s_cmp_gt_u32 s101, s71
	s_cbranch_scc1 .Lhf_exit
	s_waitcnt vmcnt(16)
	v_add_f32_e32 v72, v10, v14
	v_add_f32_e32 v73, v11, v15
	v_add_f32_e32 v74, v12, v16
	v_add_f32_e32 v75, v13, v17
	v_lshlrev_b32_e32 v84, 16, v18
	v_and_b32_e32 v85, 0xffff0000, v18
	v_lshlrev_b32_e32 v86, 16, v19
	v_and_b32_e32 v87, 0xffff0000, v19
	v_mul_f32_e32 v76, v73, v73
	v_mul_f32_e32 v77, v75, v75
	v_fmac_f32_e32 v76, v72, v72
	v_fmac_f32_e32 v77, v74, v74
	v_add_f32_e32 v78, v76, v77
	ds_bpermute_b32 v76, v67, v78
	v_mul_f32_e32 v88, 0xbfb8aa3b, v84
	v_mul_f32_e32 v89, 0xbfb8aa3b, v85
	v_mul_f32_e32 v90, 0xbfb8aa3b, v86
	v_mul_f32_e32 v91, 0xbfb8aa3b, v87
	s_waitcnt lgkmcnt(0)
	v_add_f32_e32 v78, v78, v76
	ds_bpermute_b32 v76, v68, v78
	v_exp_f32_e32 v88, v88
	v_exp_f32_e32 v89, v89
	v_exp_f32_e32 v90, v90
	v_exp_f32_e32 v91, v91
	s_waitcnt lgkmcnt(0)
	v_add_f32_e32 v78, v78, v76
	ds_bpermute_b32 v76, v69, v78
	v_add_f32_e32 v88, 1.0, v88
	v_add_f32_e32 v89, 1.0, v89
	v_add_f32_e32 v90, 1.0, v90
	v_add_f32_e32 v91, 1.0, v91
	s_waitcnt lgkmcnt(0)
	v_add_f32_e32 v78, v78, v76
	ds_bpermute_b32 v76, v70, v78
	v_rcp_f32_e32 v88, v88
	v_rcp_f32_e32 v89, v89
	v_rcp_f32_e32 v90, v90
	v_rcp_f32_e32 v91, v91
	s_waitcnt lgkmcnt(0)
	v_add_f32_e32 v78, v78, v76
	v_mul_f32_e32 v88, v88, v84
	v_mul_f32_e32 v89, v89, v85
	v_mul_f32_e32 v90, v90, v86
	v_mul_f32_e32 v91, v91, v87
	v_fmamk_f32 v78, v78, 0x3c800000, v201
	v_mul_f32_e32 v76, 0x4f800000, v78
	v_cmp_gt_f32_e32 vcc, 0xf800000, v78
	s_nop 1
	v_cndmask_b32_e32 v78, v78, v76, vcc
	v_sqrt_f32_e32 v76, v78
	s_nop 0
	v_add_u32_e32 v79, -1, v76
	v_add_u32_e32 v80, 1, v76
	v_fma_f32 v81, -v79, v76, v78
	v_fma_f32 v82, -v80, v76, v78
	v_cmp_ge_f32_e64 s[42:43], 0, v81
	s_nop 1
	v_cndmask_b32_e64 v76, v76, v79, s[42:43]
	v_cmp_lt_f32_e64 s[42:43], 0, v82
	s_nop 1
	v_cndmask_b32_e64 v76, v76, v80, s[42:43]
	v_mul_f32_e32 v79, 0x37800000, v76
	v_cndmask_b32_e32 v76, v76, v79, vcc
	v_cmp_class_f32_e32 vcc, v78, v202
	s_nop 1
	v_cndmask_b32_e32 v78, v76, v78, vcc
	v_div_scale_f32 v76, s[42:43], v78, v78, 1.0
	v_rcp_f32_e32 v79, v76
	v_div_scale_f32 v80, vcc, 1.0, v78, 1.0
	v_fma_f32 v81, -v76, v79, 1.0
	v_fmac_f32_e32 v79, v81, v79
	v_mul_f32_e32 v81, v80, v79
	v_fma_f32 v82, -v76, v81, v80
	v_fmac_f32_e32 v81, v82, v79
	v_fma_f32 v76, -v76, v81, v80
	v_div_fmas_f32 v76, v76, v79, v81
	v_div_fixup_f32 v83, v76, v78, 1.0
	v_mul_f32_e32 v92, v72, v83
	v_mul_f32_e32 v92, v60, v92
	v_mul_f32_e32 v92, v88, v92
	v_mul_f32_e32 v93, v73, v83
	v_mul_f32_e32 v93, v61, v93
	v_mul_f32_e32 v93, v89, v93
	v_mul_f32_e32 v94, v74, v83
	v_mul_f32_e32 v94, v62, v94
	v_mul_f32_e32 v94, v90, v94
	v_mul_f32_e32 v95, v75, v83
	v_mul_f32_e32 v95, v63, v95
	v_mul_f32_e32 v95, v91, v95
	v_cvt_pk_bf16_f32 v96, v92, v93
	v_cvt_pk_bf16_f32 v97, v94, v95
	s_lshl_b32 s12, s101, 11
	s_add_u32 s8, s40, s12
	s_addc_u32 s9, s41, 0
	global_store_dwordx2 v65, v[96:97], s[8:9]
	s_mul_i32 s100, s68, 6
	s_add_u32 s100, s100, s101
	s_cmp_le_u32 s100, s71
	s_cselect_b32 s100, s100, s101
	s_lshl_b32 s12, s100, 10
	s_add_u32 s8, s24, s12
	s_addc_u32 s9, s25, 0
	global_load_dwordx4 v[10:13], v64, s[8:9]
	s_add_u32 s8, s36, s12
	s_addc_u32 s9, s37, 0
	global_load_dwordx4 v[14:17], v64, s[8:9]
	s_mul_i32 s12, s100, 0x1600
	s_add_u32 s8, s38, s12
	s_addc_u32 s9, s39, 0
	global_load_dwordx2 v[18:19], v65, s[8:9]
	s_add_u32 s101, s101, s68
	s_cmp_gt_u32 s101, s71
	s_cbranch_scc1 .Lhf_exit
; __device__ __forceinline__ unsigned pk2(float lo, float hi) { f32x2_t v = {lo, hi}; bf16x2_t b = __builtin_convertvector(v, bf16x2_t); return __builtin_bit_cast(unsigned, b); }
; __device__ __forceinline__ float shx(float v, int o, int lane) { return __builtin_bit_cast(float, __builtin_amdgcn_ds_bpermute((lane ^ o) << 2, __builtin_bit_cast(int, v))); }
; __device__ __forceinline__ float sigmoidf_(float z) { return __builtin_amdgcn_rcpf(1.0f + fast_exp2(-z * LOG2E)); }
; __device__ __forceinline__ void phase_hfin(const Params& P, int l) {
;     ...
;         for (int u = 0; u < 3; ++u) {
;             const long i = i0 + u * S; const bool ok = i < total; const long rh = (ok ? i : i0) >> 4; const int h = (int)(rh & 3); const long r = rh >> 2;
;             const size_t off = (size_t)r * 256 + h * 64 + sub * 4;
;             a[u] = *(const f32x4*)(od0 + off); b2[u] = *(const f32x4*)(od1 + off);
;             gw[u] = *(const u32x2*)(proj + (size_t)r * INW + PB_G + h * 64 + sub * 4);
;         }
; #pragma unroll
;         for (int u = 0; u < 3; ++u) {
;             const long i = i0 + u * S; if (i >= total) break;
;             const long rh = i >> 4; const int h = (int)(rh & 3); const long r = rh >> 2;
;             const f32x4 o = a[u] + b2[u];
;             float ss = (o.x * o.x + o.y * o.y) + (o.z * o.z + o.w * o.w);
;             ss += shx(ss, 1, lane); ss += shx(ss, 2, lane); ss += shx(ss, 4, lane); ss += shx(ss, 8, lane);
;             const float rs = 1.0f / sqrtf(ss * (1.0f / 64.0f) + RMS_EPS);
;             const float g0 = bflo(gw[u].x), g1 = bfhi(gw[u].x), g2 = bflo(gw[u].y), g3 = bfhi(gw[u].y);
;             u32x2 w; w.x = pk2(o.x * rs * gg.x * (g0 * sigmoidf_(g0)), o.y * rs * gg.y * (g1 * sigmoidf_(g1))); w.y = pk2(o.z * rs * gg.z * (g2 * sigmoidf_(g2)), o.w * rs * gg.w * (g3 * sigmoidf_(g3)));
;             *(u32x2*)(mix + (size_t)r * DM + 256 + h * 64 + sub * 4) = w;
	s_waitcnt vmcnt(17)
	v_add_f32_e32 v72, v20, v24
	v_add_f32_e32 v73, v21, v25
	v_add_f32_e32 v74, v22, v26
	v_add_f32_e32 v75, v23, v27
	v_lshlrev_b32_e32 v84, 16, v28
	v_and_b32_e32 v85, 0xffff0000, v28
	v_lshlrev_b32_e32 v86, 16, v29
	v_and_b32_e32 v87, 0xffff0000, v29
	v_mul_f32_e32 v76, v73, v73
	v_mul_f32_e32 v77, v75, v75
	v_fmac_f32_e32 v76, v72, v72
	v_fmac_f32_e32 v77, v74, v74
	v_add_f32_e32 v78, v76, v77
	ds_bpermute_b32 v76, v67, v78
	v_mul_f32_e32 v88, 0xbfb8aa3b, v84
	v_mul_f32_e32 v89, 0xbfb8aa3b, v85
	v_mul_f32_e32 v90, 0xbfb8aa3b, v86
	v_mul_f32_e32 v91, 0xbfb8aa3b, v87
	s_waitcnt lgkmcnt(0)
	v_add_f32_e32 v78, v78, v76
	ds_bpermute_b32 v76, v68, v78
	v_exp_f32_e32 v88, v88
	v_exp_f32_e32 v89, v89
	v_exp_f32_e32 v90, v90
	v_exp_f32_e32 v91, v91
	s_waitcnt lgkmcnt(0)
	v_add_f32_e32 v78, v78, v76
	ds_bpermute_b32 v76, v69, v78
	v_add_f32_e32 v88, 1.0, v88
	v_add_f32_e32 v89, 1.0, v89
	v_add_f32_e32 v90, 1.0, v90
	v_add_f32_e32 v91, 1.0, v91
	s_waitcnt lgkmcnt(0)
	v_add_f32_e32 v78, v78, v76
	ds_bpermute_b32 v76, v70, v78
	v_rcp_f32_e32 v88, v88
	v_rcp_f32_e32 v89, v89
	v_rcp_f32_e32 v90, v90
	v_rcp_f32_e32 v91, v91
	s_waitcnt lgkmcnt(0)
	v_add_f32_e32 v78, v78, v76
	v_mul_f32_e32 v88, v88, v84
	v_mul_f32_e32 v89, v89, v85
	v_mul_f32_e32 v90, v90, v86
	v_mul_f32_e32 v91, v91, v87
	v_fmamk_f32 v78, v78, 0x3c800000, v201
	v_mul_f32_e32 v76, 0x4f800000, v78
	v_cmp_gt_f32_e32 vcc, 0xf800000, v78
	s_nop 1
	v_cndmask_b32_e32 v78, v78, v76, vcc
	v_sqrt_f32_e32 v76, v78
	s_nop 0
	v_add_u32_e32 v79, -1, v76
	v_add_u32_e32 v80, 1, v76
	v_fma_f32 v81, -v79, v76, v78
	v_fma_f32 v82, -v80, v76, v78
	v_cmp_ge_f32_e64 s[42:43], 0, v81
	s_nop 1
	v_cndmask_b32_e64 v76, v76, v79, s[42:43]
	v_cmp_lt_f32_e64 s[42:43], 0, v82
	s_nop 1
	v_cndmask_b32_e64 v76, v76, v80, s[42:43]
	v_mul_f32_e32 v79, 0x37800000, v76
	v_cndmask_b32_e32 v76, v76, v79, vcc
	v_cmp_class_f32_e32 vcc, v78, v202
	s_nop 1
	v_cndmask_b32_e32 v78, v76, v78, vcc
	v_div_scale_f32 v76, s[42:43], v78, v78, 1.0
	v_rcp_f32_e32 v79, v76
	v_div_scale_f32 v80, vcc, 1.0, v78, 1.0
	v_fma_f32 v81, -v76, v79, 1.0
	v_fmac_f32_e32 v79, v81, v79
	v_mul_f32_e32 v81, v80, v79
	v_fma_f32 v82, -v76, v81, v80
	v_fmac_f32_e32 v81, v82, v79
	v_fma_f32 v76, -v76, v81, v80
	v_div_fmas_f32 v76, v76, v79, v81
	v_div_fixup_f32 v83, v76, v78, 1.0
	v_mul_f32_e32 v92, v72, v83
	v_mul_f32_e32 v92, v60, v92
	v_mul_f32_e32 v92, v88, v92
	v_mul_f32_e32 v93, v73, v83
	v_mul_f32_e32 v93, v61, v93
	v_mul_f32_e32 v93, v89, v93
	v_mul_f32_e32 v94, v74, v83
	v_mul_f32_e32 v94, v62, v94
	v_mul_f32_e32 v94, v90, v94
	v_mul_f32_e32 v95, v75, v83
	v_mul_f32_e32 v95, v63, v95
	v_mul_f32_e32 v95, v91, v95
	v_cvt_pk_bf16_f32 v96, v92, v93
	v_cvt_pk_bf16_f32 v97, v94, v95
	s_lshl_b32 s12, s101, 11
	s_add_u32 s8, s40, s12
	s_addc_u32 s9, s41, 0
	global_store_dwordx2 v65, v[96:97], s[8:9]
	s_mul_i32 s100, s68, 6
	s_add_u32 s100, s100, s101
	s_cmp_le_u32 s100, s71
	s_cselect_b32 s100, s100, s101
	s_lshl_b32 s12, s100, 10
	s_add_u32 s8, s24, s12
	s_addc_u32 s9, s25, 0
	global_load_dwordx4 v[20:23], v64, s[8:9]
	s_add_u32 s8, s36, s12
	s_addc_u32 s9, s37, 0
	global_load_dwordx4 v[24:27], v64, s[8:9]
	s_mul_i32 s12, s100, 0x1600
	s_add_u32 s8, s38, s12
	s_addc_u32 s9, s39, 0
	global_load_dwordx2 v[28:29], v65, s[8:9]
	s_add_u32 s101, s101, s68
	s_cmp_gt_u32 s101, s71
	s_cbranch_scc1 .Lhf_exit
	s_waitcnt vmcnt(18)
	v_add_f32_e32 v72, v30, v34
	v_add_f32_e32 v73, v31, v35
	v_add_f32_e32 v74, v32, v36
	v_add_f32_e32 v75, v33, v37
	v_lshlrev_b32_e32 v84, 16, v38
	v_and_b32_e32 v85, 0xffff0000, v38
	v_lshlrev_b32_e32 v86, 16, v39
	v_and_b32_e32 v87, 0xffff0000, v39
	v_mul_f32_e32 v76, v73, v73
	v_mul_f32_e32 v77, v75, v75
	v_fmac_f32_e32 v76, v72, v72
	v_fmac_f32_e32 v77, v74, v74
	v_add_f32_e32 v78, v76, v77
	ds_bpermute_b32 v76, v67, v78
	v_mul_f32_e32 v88, 0xbfb8aa3b, v84
	v_mul_f32_e32 v89, 0xbfb8aa3b, v85
	v_mul_f32_e32 v90, 0xbfb8aa3b, v86
	v_mul_f32_e32 v91, 0xbfb8aa3b, v87
	s_waitcnt lgkmcnt(0)
	v_add_f32_e32 v78, v78, v76
	ds_bpermute_b32 v76, v68, v78
	v_exp_f32_e32 v88, v88
	v_exp_f32_e32 v89, v89
	v_exp_f32_e32 v90, v90
	v_exp_f32_e32 v91, v91
	s_waitcnt lgkmcnt(0)
	v_add_f32_e32 v78, v78, v76
	ds_bpermute_b32 v76, v69, v78
	v_add_f32_e32 v88, 1.0, v88
	v_add_f32_e32 v89, 1.0, v89
	v_add_f32_e32 v90, 1.0, v90
	v_add_f32_e32 v91, 1.0, v91
	s_waitcnt lgkmcnt(0)
	v_add_f32_e32 v78, v78, v76
	ds_bpermute_b32 v76, v70, v78
	v_rcp_f32_e32 v88, v88
	v_rcp_f32_e32 v89, v89
	v_rcp_f32_e32 v90, v90
	v_rcp_f32_e32 v91, v91
	s_waitcnt lgkmcnt(0)
	v_add_f32_e32 v78, v78, v76
	v_mul_f32_e32 v88, v88, v84
	v_mul_f32_e32 v89, v89, v85
	v_mul_f32_e32 v90, v90, v86
	v_mul_f32_e32 v91, v91, v87
	v_fmamk_f32 v78, v78, 0x3c800000, v201
	v_mul_f32_e32 v76, 0x4f800000, v78
	v_cmp_gt_f32_e32 vcc, 0xf800000, v78
	s_nop 1
	v_cndmask_b32_e32 v78, v78, v76, vcc
	v_sqrt_f32_e32 v76, v78
	s_nop 0
	v_add_u32_e32 v79, -1, v76
	v_add_u32_e32 v80, 1, v76
	v_fma_f32 v81, -v79, v76, v78
	v_fma_f32 v82, -v80, v76, v78
	v_cmp_ge_f32_e64 s[42:43], 0, v81
	s_nop 1
	v_cndmask_b32_e64 v76, v76, v79, s[42:43]
	v_cmp_lt_f32_e64 s[42:43], 0, v82
	s_nop 1
	v_cndmask_b32_e64 v76, v76, v80, s[42:43]
	v_mul_f32_e32 v79, 0x37800000, v76
	v_cndmask_b32_e32 v76, v76, v79, vcc
	v_cmp_class_f32_e32 vcc, v78, v202
	s_nop 1
	v_cndmask_b32_e32 v78, v76, v78, vcc
	v_div_scale_f32 v76, s[42:43], v78, v78, 1.0
	v_rcp_f32_e32 v79, v76
	v_div_scale_f32 v80, vcc, 1.0, v78, 1.0
	v_fma_f32 v81, -v76, v79, 1.0
	v_fmac_f32_e32 v79, v81, v79
	v_mul_f32_e32 v81, v80, v79
	v_fma_f32 v82, -v76, v81, v80
	v_fmac_f32_e32 v81, v82, v79
	v_fma_f32 v76, -v76, v81, v80
	v_div_fmas_f32 v76, v76, v79, v81
	v_div_fixup_f32 v83, v76, v78, 1.0
	v_mul_f32_e32 v92, v72, v83
	v_mul_f32_e32 v92, v60, v92
	v_mul_f32_e32 v92, v88, v92
	v_mul_f32_e32 v93, v73, v83
	v_mul_f32_e32 v93, v61, v93
	v_mul_f32_e32 v93, v89, v93
	v_mul_f32_e32 v94, v74, v83
	v_mul_f32_e32 v94, v62, v94
	v_mul_f32_e32 v94, v90, v94
	v_mul_f32_e32 v95, v75, v83
	v_mul_f32_e32 v95, v63, v95
	v_mul_f32_e32 v95, v91, v95
	v_cvt_pk_bf16_f32 v96, v92, v93
	v_cvt_pk_bf16_f32 v97, v94, v95
	s_lshl_b32 s12, s101, 11
	s_add_u32 s8, s40, s12
	s_addc_u32 s9, s41, 0
	global_store_dwordx2 v65, v[96:97], s[8:9]
	s_mul_i32 s100, s68, 6
	s_add_u32 s100, s100, s101
	s_cmp_le_u32 s100, s71
	s_cselect_b32 s100, s100, s101
	s_lshl_b32 s12, s100, 10
	s_add_u32 s8, s24, s12
	s_addc_u32 s9, s25, 0
	global_load_dwordx4 v[30:33], v64, s[8:9]
	s_add_u32 s8, s36, s12
	s_addc_u32 s9, s37, 0
	global_load_dwordx4 v[34:37], v64, s[8:9]
	s_mul_i32 s12, s100, 0x1600
	s_add_u32 s8, s38, s12
	s_addc_u32 s9, s39, 0
	global_load_dwordx2 v[38:39], v65, s[8:9]
	s_add_u32 s101, s101, s68
	s_cmp_gt_u32 s101, s71
	s_cbranch_scc1 .Lhf_exit
; __device__ __forceinline__ unsigned pk2(float lo, float hi) { f32x2_t v = {lo, hi}; bf16x2_t b = __builtin_convertvector(v, bf16x2_t); return __builtin_bit_cast(unsigned, b); }
; __device__ __forceinline__ float shx(float v, int o, int lane) { return __builtin_bit_cast(float, __builtin_amdgcn_ds_bpermute((lane ^ o) << 2, __builtin_bit_cast(int, v))); }
; __device__ __forceinline__ float sigmoidf_(float z) { return __builtin_amdgcn_rcpf(1.0f + fast_exp2(-z * LOG2E)); }
; __device__ __forceinline__ void phase_hfin(const Params& P, int l) {
;     ...
;         for (int u = 0; u < 3; ++u) {
;             const long i = i0 + u * S; const bool ok = i < total; const long rh = (ok ? i : i0) >> 4; const int h = (int)(rh & 3); const long r = rh >> 2;
;             const size_t off = (size_t)r * 256 + h * 64 + sub * 4;
;             a[u] = *(const f32x4*)(od0 + off); b2[u] = *(const f32x4*)(od1 + off);
;             gw[u] = *(const u32x2*)(proj + (size_t)r * INW + PB_G + h * 64 + sub * 4);
;         }
; #pragma unroll
;         for (int u = 0; u < 3; ++u) {
;             const long i = i0 + u * S; if (i >= total) break;
;             const long rh = i >> 4; const int h = (int)(rh & 3); const long r = rh >> 2;
;             const f32x4 o = a[u] + b2[u];
;             float ss = (o.x * o.x + o.y * o.y) + (o.z * o.z + o.w * o.w);
;             ss += shx(ss, 1, lane); ss += shx(ss, 2, lane); ss += shx(ss, 4, lane); ss += shx(ss, 8, lane);
;             const float rs = 1.0f / sqrtf(ss * (1.0f / 64.0f) + RMS_EPS);
;             const float g0 = bflo(gw[u].x), g1 = bfhi(gw[u].x), g2 = bflo(gw[u].y), g3 = bfhi(gw[u].y);
;             u32x2 w; w.x = pk2(o.x * rs * gg.x * (g0 * sigmoidf_(g0)), o.y * rs * gg.y * (g1 * sigmoidf_(g1))); w.y = pk2(o.z * rs * gg.z * (g2 * sigmoidf_(g2)), o.w * rs * gg.w * (g3 * sigmoidf_(g3)));
;             *(u32x2*)(mix + (size_t)r * DM + 256 + h * 64 + sub * 4) = w;
	s_waitcnt vmcnt(19)
	v_add_f32_e32 v72, v40, v44
	v_add_f32_e32 v73, v41, v45
	v_add_f32_e32 v74, v42, v46
	v_add_f32_e32 v75, v43, v47
	v_lshlrev_b32_e32 v84, 16, v48
	v_and_b32_e32 v85, 0xffff0000, v48
	v_lshlrev_b32_e32 v86, 16, v49
	v_and_b32_e32 v87, 0xffff0000, v49
	v_mul_f32_e32 v76, v73, v73
	v_mul_f32_e32 v77, v75, v75
	v_fmac_f32_e32 v76, v72, v72
	v_fmac_f32_e32 v77, v74, v74
	v_add_f32_e32 v78, v76, v77
	ds_bpermute_b32 v76, v67, v78
	v_mul_f32_e32 v88, 0xbfb8aa3b, v84
	v_mul_f32_e32 v89, 0xbfb8aa3b, v85
	v_mul_f32_e32 v90, 0xbfb8aa3b, v86
	v_mul_f32_e32 v91, 0xbfb8aa3b, v87
	s_waitcnt lgkmcnt(0)
	v_add_f32_e32 v78, v78, v76
	ds_bpermute_b32 v76, v68, v78
	v_exp_f32_e32 v88, v88
	v_exp_f32_e32 v89, v89
	v_exp_f32_e32 v90, v90
	v_exp_f32_e32 v91, v91
	s_waitcnt lgkmcnt(0)
	v_add_f32_e32 v78, v78, v76
	ds_bpermute_b32 v76, v69, v78
	v_add_f32_e32 v88, 1.0, v88
	v_add_f32_e32 v89, 1.0, v89
	v_add_f32_e32 v90, 1.0, v90
	v_add_f32_e32 v91, 1.0, v91
	s_waitcnt lgkmcnt(0)
	v_add_f32_e32 v78, v78, v76
	ds_bpermute_b32 v76, v70, v78
	v_rcp_f32_e32 v88, v88
	v_rcp_f32_e32 v89, v89
	v_rcp_f32_e32 v90, v90
	v_rcp_f32_e32 v91, v91
	s_waitcnt lgkmcnt(0)
	v_add_f32_e32 v78, v78, v76
	v_mul_f32_e32 v88, v88, v84
	v_mul_f32_e32 v89, v89, v85
	v_mul_f32_e32 v90, v90, v86
	v_mul_f32_e32 v91, v91, v87
	v_fmamk_f32 v78, v78, 0x3c800000, v201
	v_mul_f32_e32 v76, 0x4f800000, v78
	v_cmp_gt_f32_e32 vcc, 0xf800000, v78
	s_nop 1
	v_cndmask_b32_e32 v78, v78, v76, vcc
	v_sqrt_f32_e32 v76, v78
	s_nop 0
	v_add_u32_e32 v79, -1, v76
	v_add_u32_e32 v80, 1, v76
	v_fma_f32 v81, -v79, v76, v78
	v_fma_f32 v82, -v80, v76, v78
	v_cmp_ge_f32_e64 s[42:43], 0, v81
	s_nop 1
	v_cndmask_b32_e64 v76, v76, v79, s[42:43]
	v_cmp_lt_f32_e64 s[42:43], 0, v82
	s_nop 1
	v_cndmask_b32_e64 v76, v76, v80, s[42:43]
	v_mul_f32_e32 v79, 0x37800000, v76
	v_cndmask_b32_e32 v76, v76, v79, vcc
	v_cmp_class_f32_e32 vcc, v78, v202
	s_nop 1
	v_cndmask_b32_e32 v78, v76, v78, vcc
	v_div_scale_f32 v76, s[42:43], v78, v78, 1.0
	v_rcp_f32_e32 v79, v76
	v_div_scale_f32 v80, vcc, 1.0, v78, 1.0
	v_fma_f32 v81, -v76, v79, 1.0
	v_fmac_f32_e32 v79, v81, v79
	v_mul_f32_e32 v81, v80, v79
	v_fma_f32 v82, -v76, v81, v80
	v_fmac_f32_e32 v81, v82, v79
	v_fma_f32 v76, -v76, v81, v80
	v_div_fmas_f32 v76, v76, v79, v81
	v_div_fixup_f32 v83, v76, v78, 1.0
	v_mul_f32_e32 v92, v72, v83
	v_mul_f32_e32 v92, v60, v92
	v_mul_f32_e32 v92, v88, v92
	v_mul_f32_e32 v93, v73, v83
	v_mul_f32_e32 v93, v61, v93
	v_mul_f32_e32 v93, v89, v93
	v_mul_f32_e32 v94, v74, v83
	v_mul_f32_e32 v94, v62, v94
	v_mul_f32_e32 v94, v90, v94
	v_mul_f32_e32 v95, v75, v83
	v_mul_f32_e32 v95, v63, v95
	v_mul_f32_e32 v95, v91, v95
	v_cvt_pk_bf16_f32 v96, v92, v93
	v_cvt_pk_bf16_f32 v97, v94, v95
	s_lshl_b32 s12, s101, 11
	s_add_u32 s8, s40, s12
	s_addc_u32 s9, s41, 0
	global_store_dwordx2 v65, v[96:97], s[8:9]
	s_mul_i32 s100, s68, 6
	s_add_u32 s100, s100, s101
	s_cmp_le_u32 s100, s71
	s_cselect_b32 s100, s100, s101
	s_lshl_b32 s12, s100, 10
	s_add_u32 s8, s24, s12
	s_addc_u32 s9, s25, 0
	global_load_dwordx4 v[40:43], v64, s[8:9]
	s_add_u32 s8, s36, s12
	s_addc_u32 s9, s37, 0
	global_load_dwordx4 v[44:47], v64, s[8:9]
	s_mul_i32 s12, s100, 0x1600
	s_add_u32 s8, s38, s12
	s_addc_u32 s9, s39, 0
	global_load_dwordx2 v[48:49], v65, s[8:9]
	s_add_u32 s101, s101, s68
	s_cmp_gt_u32 s101, s71
	s_cbranch_scc1 .Lhf_exit
	s_waitcnt vmcnt(20)
	v_add_f32_e32 v72, v50, v54
	v_add_f32_e32 v73, v51, v55
	v_add_f32_e32 v74, v52, v56
	v_add_f32_e32 v75, v53, v57
	v_lshlrev_b32_e32 v84, 16, v58
	v_and_b32_e32 v85, 0xffff0000, v58
	v_lshlrev_b32_e32 v86, 16, v59
	v_and_b32_e32 v87, 0xffff0000, v59
	v_mul_f32_e32 v76, v73, v73
	v_mul_f32_e32 v77, v75, v75
	v_fmac_f32_e32 v76, v72, v72
	v_fmac_f32_e32 v77, v74, v74
	v_add_f32_e32 v78, v76, v77
	ds_bpermute_b32 v76, v67, v78
	v_mul_f32_e32 v88, 0xbfb8aa3b, v84
	v_mul_f32_e32 v89, 0xbfb8aa3b, v85
	v_mul_f32_e32 v90, 0xbfb8aa3b, v86
	v_mul_f32_e32 v91, 0xbfb8aa3b, v87
	s_waitcnt lgkmcnt(0)
	v_add_f32_e32 v78, v78, v76
	ds_bpermute_b32 v76, v68, v78
	v_exp_f32_e32 v88, v88
	v_exp_f32_e32 v89, v89
	v_exp_f32_e32 v90, v90
	v_exp_f32_e32 v91, v91
	s_waitcnt lgkmcnt(0)
	v_add_f32_e32 v78, v78, v76
	ds_bpermute_b32 v76, v69, v78
	v_add_f32_e32 v88, 1.0, v88
	v_add_f32_e32 v89, 1.0, v89
	v_add_f32_e32 v90, 1.0, v90
	v_add_f32_e32 v91, 1.0, v91
	s_waitcnt lgkmcnt(0)
	v_add_f32_e32 v78, v78, v76
	ds_bpermute_b32 v76, v70, v78
	v_rcp_f32_e32 v88, v88
	v_rcp_f32_e32 v89, v89
	v_rcp_f32_e32 v90, v90
	v_rcp_f32_e32 v91, v91
	s_waitcnt lgkmcnt(0)
	v_add_f32_e32 v78, v78, v76
	v_mul_f32_e32 v88, v88, v84
	v_mul_f32_e32 v89, v89, v85
	v_mul_f32_e32 v90, v90, v86
	v_mul_f32_e32 v91, v91, v87
	v_fmamk_f32 v78, v78, 0x3c800000, v201
	v_mul_f32_e32 v76, 0x4f800000, v78
	v_cmp_gt_f32_e32 vcc, 0xf800000, v78
	s_nop 1
	v_cndmask_b32_e32 v78, v78, v76, vcc
	v_sqrt_f32_e32 v76, v78
	s_nop 0
	v_add_u32_e32 v79, -1, v76
	v_add_u32_e32 v80, 1, v76
	v_fma_f32 v81, -v79, v76, v78
	v_fma_f32 v82, -v80, v76, v78
	v_cmp_ge_f32_e64 s[42:43], 0, v81
	s_nop 1
	v_cndmask_b32_e64 v76, v76, v79, s[42:43]
	v_cmp_lt_f32_e64 s[42:43], 0, v82
	s_nop 1
	v_cndmask_b32_e64 v76, v76, v80, s[42:43]
	v_mul_f32_e32 v79, 0x37800000, v76
	v_cndmask_b32_e32 v76, v76, v79, vcc
	v_cmp_class_f32_e32 vcc, v78, v202
	s_nop 1
	v_cndmask_b32_e32 v78, v76, v78, vcc
	v_div_scale_f32 v76, s[42:43], v78, v78, 1.0
	v_rcp_f32_e32 v79, v76
	v_div_scale_f32 v80, vcc, 1.0, v78, 1.0
	v_fma_f32 v81, -v76, v79, 1.0
	v_fmac_f32_e32 v79, v81, v79
	v_mul_f32_e32 v81, v80, v79
	v_fma_f32 v82, -v76, v81, v80
	v_fmac_f32_e32 v81, v82, v79
	v_fma_f32 v76, -v76, v81, v80
	v_div_fmas_f32 v76, v76, v79, v81
	v_div_fixup_f32 v83, v76, v78, 1.0
	v_mul_f32_e32 v92, v72, v83
	v_mul_f32_e32 v92, v60, v92
	v_mul_f32_e32 v92, v88, v92
	v_mul_f32_e32 v93, v73, v83
	v_mul_f32_e32 v93, v61, v93
	v_mul_f32_e32 v93, v89, v93
	v_mul_f32_e32 v94, v74, v83
	v_mul_f32_e32 v94, v62, v94
	v_mul_f32_e32 v94, v90, v94
	v_mul_f32_e32 v95, v75, v83
	v_mul_f32_e32 v95, v63, v95
	v_mul_f32_e32 v95, v91, v95
	v_cvt_pk_bf16_f32 v96, v92, v93
	v_cvt_pk_bf16_f32 v97, v94, v95
	s_lshl_b32 s12, s101, 11
	s_add_u32 s8, s40, s12
	s_addc_u32 s9, s41, 0
	global_store_dwordx2 v65, v[96:97], s[8:9]
	s_mul_i32 s100, s68, 6
	s_add_u32 s100, s100, s101
	s_cmp_le_u32 s100, s71
	s_cselect_b32 s100, s100, s101
	s_lshl_b32 s12, s100, 10
	s_add_u32 s8, s24, s12
	s_addc_u32 s9, s25, 0
	global_load_dwordx4 v[50:53], v64, s[8:9]
	s_add_u32 s8, s36, s12
	s_addc_u32 s9, s37, 0
	global_load_dwordx4 v[54:57], v64, s[8:9]
	s_mul_i32 s12, s100, 0x1600
	s_add_u32 s8, s38, s12
	s_addc_u32 s9, s39, 0
	global_load_dwordx2 v[58:59], v65, s[8:9]
	s_add_u32 s101, s101, s68
	s_cmp_gt_u32 s101, s71
	s_cbranch_scc1 .Lhf_exit
